# S5 deferred stores; FF1 nt stores; hyena filter w3 loop double-buffered prefetch
# speedup vs baseline: 1.0312x; 1.0085x over previous
; DI unsigned pack2(float a, float b) { f32x2_t v = {a, b}; bf16x2_t r = __builtin_convertvector(v, bf16x2_t); return __builtin_bit_cast(unsigned, r); }
; DI bfu* wsb(const PX& p, size_t off) { return (bfu*)(p.ws + off); }
; template <int EPI, int HM>
; DI void epi256(const PX& p, int l, f32x4 (&acc)[2][2][4][2], int brow, int bcol, int aux, bool src_input) {
;     ...
;           } else if (EPI == EPI_FF1) {
;             float t[8];
; #pragma unroll
;             for (int j = 0; j < 8; j++) { t[j] = fmaxf(v[j], 0.f); t[j] *= t[j]; }
;             uint4 o; o.x = pack2(t[0], t[1]); o.y = pack2(t[2], t[3]); o.z = pack2(t[4], t[5]); o.w = pack2(t[6], t[7]);
;             *(uint4*)(wsb(p, OFF_BIG) + (size_t)row * 8192 + col0) = o;
.LBB0_72:
	v_mov_b32_e32 v0, v188
	v_readlane_b32 s8, v253, 29
	v_ashrrev_i32_e32 v131, 2, v0
	v_and_b32_e32 v130, 15, v0
	v_and_b32_e32 v131, 0xffffffc0, v131
	v_lshrrev_b32_e32 v0, 1, v0
	v_add3_u32 v130, v130, s16, v131
	v_and_b32_e32 v131, 0x60, v0
	v_and_b32_e32 v0, 24, v0
	v_add3_u32 v132, v131, s14, v0
	v_max_f32_e32 v0, v126, v126
	v_max_f32_e32 v126, 0, v0
	v_max_f32_e32 v0, v127, v127
	v_max_f32_e32 v127, 0, v0
	v_max_f32_e32 v0, v128, v128
	v_max_f32_e32 v128, 0, v0
	v_max_f32_e32 v0, v129, v129
	v_max_f32_e32 v129, 0, v0
	v_max_f32_e32 v0, v122, v122
	v_max_f32_e32 v122, 0, v0
	v_max_f32_e32 v0, v123, v123
	v_max_f32_e32 v123, 0, v0
	v_max_f32_e32 v0, v124, v124
	v_max_f32_e32 v124, 0, v0
	v_max_f32_e32 v0, v125, v125
	v_max_f32_e32 v125, 0, v0
	v_max_f32_e32 v0, v118, v118
	v_max_f32_e32 v118, 0, v0
	v_max_f32_e32 v0, v119, v119
	v_max_f32_e32 v119, 0, v0
	v_max_f32_e32 v0, v120, v120
	v_pk_mul_f32 v[126:127], v[126:127], v[126:127]
	v_pk_mul_f32 v[122:123], v[122:123], v[122:123]
	v_ashrrev_i32_e32 v131, 31, v130
	v_max_f32_e32 v120, 0, v0
	v_max_f32_e32 v0, v121, v121
	v_ashrrev_i32_e32 v133, 31, v132
	v_pk_mul_f32 v[128:129], v[128:129], v[128:129]
	v_pk_mul_f32 v[134:135], v[124:125], v[124:125]
	v_cvt_pk_bf16_f32 v124, v126, v127
	v_cvt_pk_bf16_f32 v126, v122, v123
	v_lshlrev_b64 v[122:123], 14, v[130:131]
	v_readlane_b32 s9, v253, 30
	v_max_f32_e32 v121, 0, v0
	v_max_f32_e32 v0, v114, v114
	v_cvt_pk_bf16_f32 v125, v128, v129
	v_lshl_add_u64 v[128:129], s[8:9], 0, v[122:123]
	v_lshlrev_b64 v[122:123], 1, v[132:133]
	v_max_f32_e32 v114, 0, v0
	v_max_f32_e32 v0, v115, v115
	v_cvt_pk_bf16_f32 v127, v134, v135
	v_lshl_add_u64 v[128:129], v[128:129], 0, v[122:123]
	v_max_f32_e32 v115, 0, v0
	v_max_f32_e32 v0, v116, v116
	global_store_dwordx4 v[128:129], v[124:127], off nt
	v_add_u32_e32 v132, 16, v130
	v_pk_mul_f32 v[118:119], v[118:119], v[118:119]
	v_pk_mul_f32 v[124:125], v[114:115], v[114:115]
	v_max_f32_e32 v114, 0, v0
	v_max_f32_e32 v0, v117, v117
	v_max_f32_e32 v115, 0, v0
	v_max_f32_e32 v0, v110, v110
	v_max_f32_e32 v110, 0, v0
	v_max_f32_e32 v0, v111, v111
	v_max_f32_e32 v111, 0, v0
	v_max_f32_e32 v0, v112, v112
	v_ashrrev_i32_e32 v133, 31, v132
	v_max_f32_e32 v112, 0, v0
	v_max_f32_e32 v0, v113, v113
	v_pk_mul_f32 v[126:127], v[114:115], v[114:115]
	v_cvt_pk_bf16_f32 v114, v118, v119
	v_lshlrev_b64 v[118:119], 14, v[132:133]
	v_max_f32_e32 v113, 0, v0
	v_max_f32_e32 v0, v106, v106
	v_pk_mul_f32 v[120:121], v[120:121], v[120:121]
	v_lshl_add_u64 v[118:119], s[8:9], 0, v[118:119]
	v_max_f32_e32 v106, 0, v0
	v_max_f32_e32 v0, v107, v107
	v_cvt_pk_bf16_f32 v115, v120, v121
	v_cvt_pk_bf16_f32 v116, v124, v125
	v_cvt_pk_bf16_f32 v117, v126, v127
	v_lshl_add_u64 v[118:119], v[118:119], 0, v[122:123]
	v_max_f32_e32 v107, 0, v0
	v_max_f32_e32 v0, v108, v108
	global_store_dwordx4 v[118:119], v[114:117], off nt
	v_add_u32_e32 v120, 32, v130
	v_pk_mul_f32 v[110:111], v[110:111], v[110:111]
	v_pk_mul_f32 v[114:115], v[106:107], v[106:107]
	v_max_f32_e32 v106, 0, v0
	v_max_f32_e32 v0, v109, v109
	v_max_f32_e32 v107, 0, v0
	v_max_f32_e32 v0, v102, v102
	v_max_f32_e32 v102, 0, v0
	v_max_f32_e32 v0, v103, v103
	v_max_f32_e32 v103, 0, v0
	v_max_f32_e32 v0, v104, v104
	v_ashrrev_i32_e32 v121, 31, v120
	v_max_f32_e32 v104, 0, v0
	v_max_f32_e32 v0, v105, v105
	v_pk_mul_f32 v[116:117], v[106:107], v[106:107]
	v_cvt_pk_bf16_f32 v106, v110, v111
	v_lshlrev_b64 v[110:111], 14, v[120:121]
	v_max_f32_e32 v105, 0, v0
	v_max_f32_e32 v0, v98, v98
	v_pk_mul_f32 v[112:113], v[112:113], v[112:113]
	v_lshl_add_u64 v[110:111], s[8:9], 0, v[110:111]
	v_max_f32_e32 v98, 0, v0
	v_max_f32_e32 v0, v99, v99
	v_cvt_pk_bf16_f32 v107, v112, v113
	v_cvt_pk_bf16_f32 v108, v114, v115
	v_cvt_pk_bf16_f32 v109, v116, v117
	v_lshl_add_u64 v[110:111], v[110:111], 0, v[122:123]
	v_max_f32_e32 v99, 0, v0
	v_max_f32_e32 v0, v100, v100
	global_store_dwordx4 v[110:111], v[106:109], off nt
	v_add_u32_e32 v112, 48, v130
	v_pk_mul_f32 v[102:103], v[102:103], v[102:103]
	v_pk_mul_f32 v[106:107], v[98:99], v[98:99]
	v_max_f32_e32 v98, 0, v0
	v_max_f32_e32 v0, v101, v101
	v_max_f32_e32 v99, 0, v0
	v_max_f32_e32 v0, v94, v94
	v_max_f32_e32 v94, 0, v0
	v_max_f32_e32 v0, v95, v95
	v_max_f32_e32 v95, 0, v0
	v_max_f32_e32 v0, v96, v96
	v_ashrrev_i32_e32 v113, 31, v112
	v_max_f32_e32 v96, 0, v0
	v_max_f32_e32 v0, v97, v97
	v_pk_mul_f32 v[108:109], v[98:99], v[98:99]
	v_cvt_pk_bf16_f32 v98, v102, v103
	v_lshlrev_b64 v[102:103], 14, v[112:113]
	v_max_f32_e32 v97, 0, v0
	v_max_f32_e32 v0, v90, v90
	v_pk_mul_f32 v[104:105], v[104:105], v[104:105]
	v_lshl_add_u64 v[102:103], s[8:9], 0, v[102:103]
	v_max_f32_e32 v90, 0, v0
	v_max_f32_e32 v0, v91, v91
	v_cvt_pk_bf16_f32 v99, v104, v105
	v_cvt_pk_bf16_f32 v100, v106, v107
	v_cvt_pk_bf16_f32 v101, v108, v109
	v_lshl_add_u64 v[102:103], v[102:103], 0, v[122:123]
	v_max_f32_e32 v91, 0, v0
	v_max_f32_e32 v0, v92, v92
	global_store_dwordx4 v[102:103], v[98:101], off nt
	v_pk_mul_f32 v[94:95], v[94:95], v[94:95]
	v_pk_mul_f32 v[96:97], v[96:97], v[96:97]
	v_pk_mul_f32 v[98:99], v[90:91], v[90:91]
	v_max_f32_e32 v90, 0, v0
	v_max_f32_e32 v0, v93, v93
	v_max_f32_e32 v91, 0, v0
	v_max_f32_e32 v0, v86, v86
	v_max_f32_e32 v86, 0, v0
	v_max_f32_e32 v0, v87, v87
	v_max_f32_e32 v87, 0, v0
	v_max_f32_e32 v0, v88, v88
	v_max_f32_e32 v88, 0, v0
	v_max_f32_e32 v0, v89, v89
	v_max_f32_e32 v89, 0, v0
	v_max_f32_e32 v0, v82, v82
	v_pk_mul_f32 v[100:101], v[90:91], v[90:91]
	v_max_f32_e32 v82, 0, v0
	v_max_f32_e32 v0, v83, v83
	v_cvt_pk_bf16_f32 v90, v94, v95
	v_cvt_pk_bf16_f32 v91, v96, v97
	v_cvt_pk_bf16_f32 v92, v98, v99
	v_cvt_pk_bf16_f32 v93, v100, v101
; DI unsigned pack2(float a, float b) { f32x2_t v = {a, b}; bf16x2_t r = __builtin_convertvector(v, bf16x2_t); return __builtin_bit_cast(unsigned, r); }
; DI bfu* wsb(const PX& p, size_t off) { return (bfu*)(p.ws + off); }
; template <int EPI, int HM>
; DI void epi256(const PX& p, int l, f32x4 (&acc)[2][2][4][2], int brow, int bcol, int aux, bool src_input) {
;     ...
;           } else if (EPI == EPI_FF1) {
;             float t[8];
; #pragma unroll
;             for (int j = 0; j < 8; j++) { t[j] = fmaxf(v[j], 0.f); t[j] *= t[j]; }
;             uint4 o; o.x = pack2(t[0], t[1]); o.y = pack2(t[2], t[3]); o.z = pack2(t[4], t[5]); o.w = pack2(t[6], t[7]);
;             *(uint4*)(wsb(p, OFF_BIG) + (size_t)row * 8192 + col0) = o;
	v_max_f32_e32 v83, 0, v0
	v_max_f32_e32 v0, v84, v84
	global_store_dwordx4 v[128:129], v[90:93], off offset:256 nt
	v_pk_mul_f32 v[86:87], v[86:87], v[86:87]
	v_pk_mul_f32 v[88:89], v[88:89], v[88:89]
	v_pk_mul_f32 v[90:91], v[82:83], v[82:83]
	v_max_f32_e32 v82, 0, v0
	v_max_f32_e32 v0, v85, v85
	v_max_f32_e32 v83, 0, v0
	v_max_f32_e32 v0, v78, v78
	v_max_f32_e32 v78, 0, v0
	v_max_f32_e32 v0, v79, v79
	v_max_f32_e32 v79, 0, v0
	v_max_f32_e32 v0, v80, v80
	v_max_f32_e32 v80, 0, v0
	v_max_f32_e32 v0, v81, v81
	v_max_f32_e32 v81, 0, v0
	v_max_f32_e32 v0, v74, v74
	v_pk_mul_f32 v[92:93], v[82:83], v[82:83]
	v_max_f32_e32 v74, 0, v0
	v_max_f32_e32 v0, v75, v75
	v_cvt_pk_bf16_f32 v82, v86, v87
	v_cvt_pk_bf16_f32 v83, v88, v89
	v_cvt_pk_bf16_f32 v84, v90, v91
	v_cvt_pk_bf16_f32 v85, v92, v93
	v_max_f32_e32 v75, 0, v0
	v_max_f32_e32 v0, v76, v76
	global_store_dwordx4 v[118:119], v[82:85], off offset:256 nt
	v_pk_mul_f32 v[78:79], v[78:79], v[78:79]
	v_pk_mul_f32 v[80:81], v[80:81], v[80:81]
	v_pk_mul_f32 v[82:83], v[74:75], v[74:75]
	v_max_f32_e32 v74, 0, v0
	v_max_f32_e32 v0, v77, v77
	v_max_f32_e32 v75, 0, v0
	v_max_f32_e32 v0, v70, v70
	v_max_f32_e32 v70, 0, v0
	v_max_f32_e32 v0, v71, v71
	v_max_f32_e32 v71, 0, v0
	v_max_f32_e32 v0, v72, v72
	v_max_f32_e32 v72, 0, v0
	v_max_f32_e32 v0, v73, v73
	v_max_f32_e32 v73, 0, v0
	v_max_f32_e32 v0, v66, v66
	v_pk_mul_f32 v[84:85], v[74:75], v[74:75]
	v_max_f32_e32 v66, 0, v0
	v_max_f32_e32 v0, v67, v67
	v_cvt_pk_bf16_f32 v74, v78, v79
	v_cvt_pk_bf16_f32 v75, v80, v81
	v_cvt_pk_bf16_f32 v76, v82, v83
	v_cvt_pk_bf16_f32 v77, v84, v85
	v_max_f32_e32 v67, 0, v0
	v_max_f32_e32 v0, v68, v68
	global_store_dwordx4 v[110:111], v[74:77], off offset:256 nt
	v_pk_mul_f32 v[70:71], v[70:71], v[70:71]
	v_pk_mul_f32 v[72:73], v[72:73], v[72:73]
	v_pk_mul_f32 v[74:75], v[66:67], v[66:67]
	v_max_f32_e32 v66, 0, v0
	v_max_f32_e32 v0, v69, v69
	v_max_f32_e32 v67, 0, v0
	v_max_f32_e32 v0, v62, v62
	v_max_f32_e32 v62, 0, v0
	v_max_f32_e32 v0, v63, v63
	v_max_f32_e32 v63, 0, v0
	v_max_f32_e32 v0, v64, v64
	v_max_f32_e32 v64, 0, v0
	v_max_f32_e32 v0, v65, v65
	v_max_f32_e32 v65, 0, v0
	v_max_f32_e32 v0, v58, v58
	v_pk_mul_f32 v[76:77], v[66:67], v[66:67]
	v_max_f32_e32 v58, 0, v0
	v_max_f32_e32 v0, v59, v59
	v_cvt_pk_bf16_f32 v66, v70, v71
	v_cvt_pk_bf16_f32 v67, v72, v73
	v_cvt_pk_bf16_f32 v68, v74, v75
	v_cvt_pk_bf16_f32 v69, v76, v77
	v_max_f32_e32 v59, 0, v0
	v_max_f32_e32 v0, v60, v60
	global_store_dwordx4 v[102:103], v[66:69], off offset:256 nt
	v_pk_mul_f32 v[62:63], v[62:63], v[62:63]
	v_pk_mul_f32 v[64:65], v[64:65], v[64:65]
	v_pk_mul_f32 v[68:69], v[58:59], v[58:59]
	v_max_f32_e32 v58, 0, v0
	v_max_f32_e32 v0, v61, v61
	v_max_f32_e32 v59, 0, v0
	v_max_f32_e32 v0, v54, v54
	v_max_f32_e32 v54, 0, v0
	v_max_f32_e32 v0, v55, v55
	v_add_u32_e32 v66, 0x80, v130
	v_max_f32_e32 v55, 0, v0
	v_max_f32_e32 v0, v56, v56
	v_ashrrev_i32_e32 v67, 31, v66
	v_max_f32_e32 v56, 0, v0
	v_max_f32_e32 v0, v57, v57
	v_pk_mul_f32 v[70:71], v[58:59], v[58:59]
	v_cvt_pk_bf16_f32 v58, v62, v63
	v_lshlrev_b64 v[62:63], 14, v[66:67]
	v_max_f32_e32 v57, 0, v0
	v_max_f32_e32 v0, v50, v50
	v_lshl_add_u64 v[62:63], s[8:9], 0, v[62:63]
	v_max_f32_e32 v50, 0, v0
	v_max_f32_e32 v0, v51, v51
	v_cvt_pk_bf16_f32 v59, v64, v65
	v_cvt_pk_bf16_f32 v60, v68, v69
	v_cvt_pk_bf16_f32 v61, v70, v71
	v_lshl_add_u64 v[62:63], v[62:63], 0, v[122:123]
	v_max_f32_e32 v51, 0, v0
	v_max_f32_e32 v0, v52, v52
	global_store_dwordx4 v[62:63], v[58:61], off nt
	v_add_u32_e32 v64, 0x90, v130
	v_pk_mul_f32 v[54:55], v[54:55], v[54:55]
	v_pk_mul_f32 v[58:59], v[50:51], v[50:51]
	v_max_f32_e32 v50, 0, v0
	v_max_f32_e32 v0, v53, v53
	v_max_f32_e32 v51, 0, v0
	v_max_f32_e32 v0, v46, v46
	v_max_f32_e32 v46, 0, v0
	v_max_f32_e32 v0, v47, v47
	v_max_f32_e32 v47, 0, v0
	v_max_f32_e32 v0, v48, v48
	v_ashrrev_i32_e32 v65, 31, v64
	v_max_f32_e32 v48, 0, v0
	v_max_f32_e32 v0, v49, v49
	v_pk_mul_f32 v[60:61], v[50:51], v[50:51]
	v_cvt_pk_bf16_f32 v50, v54, v55
	v_lshlrev_b64 v[54:55], 14, v[64:65]
	v_max_f32_e32 v49, 0, v0
	v_max_f32_e32 v0, v42, v42
	v_pk_mul_f32 v[56:57], v[56:57], v[56:57]
	v_lshl_add_u64 v[54:55], s[8:9], 0, v[54:55]
	v_max_f32_e32 v42, 0, v0
	v_max_f32_e32 v0, v43, v43
	v_cvt_pk_bf16_f32 v51, v56, v57
	v_cvt_pk_bf16_f32 v52, v58, v59
	v_cvt_pk_bf16_f32 v53, v60, v61
	v_lshl_add_u64 v[54:55], v[54:55], 0, v[122:123]
	v_max_f32_e32 v43, 0, v0
	v_max_f32_e32 v0, v44, v44
	global_store_dwordx4 v[54:55], v[50:53], off nt
	v_add_u32_e32 v56, 0xa0, v130
	v_pk_mul_f32 v[46:47], v[46:47], v[46:47]
	v_pk_mul_f32 v[50:51], v[42:43], v[42:43]
	v_max_f32_e32 v42, 0, v0
	v_max_f32_e32 v0, v45, v45
; DI unsigned pack2(float a, float b) { f32x2_t v = {a, b}; bf16x2_t r = __builtin_convertvector(v, bf16x2_t); return __builtin_bit_cast(unsigned, r); }
; DI bfu* wsb(const PX& p, size_t off) { return (bfu*)(p.ws + off); }
; template <int EPI, int HM>
; DI void epi256(const PX& p, int l, f32x4 (&acc)[2][2][4][2], int brow, int bcol, int aux, bool src_input) {
;     ...
;           } else if (EPI == EPI_FF1) {
;             float t[8];
; #pragma unroll
;             for (int j = 0; j < 8; j++) { t[j] = fmaxf(v[j], 0.f); t[j] *= t[j]; }
;             uint4 o; o.x = pack2(t[0], t[1]); o.y = pack2(t[2], t[3]); o.z = pack2(t[4], t[5]); o.w = pack2(t[6], t[7]);
;             *(uint4*)(wsb(p, OFF_BIG) + (size_t)row * 8192 + col0) = o;
	v_max_f32_e32 v43, 0, v0
	v_max_f32_e32 v0, v38, v38
	v_max_f32_e32 v38, 0, v0
	v_max_f32_e32 v0, v39, v39
	v_max_f32_e32 v39, 0, v0
	v_max_f32_e32 v0, v40, v40
	v_ashrrev_i32_e32 v57, 31, v56
	v_max_f32_e32 v40, 0, v0
	v_max_f32_e32 v0, v41, v41
	v_pk_mul_f32 v[52:53], v[42:43], v[42:43]
	v_cvt_pk_bf16_f32 v42, v46, v47
	v_lshlrev_b64 v[46:47], 14, v[56:57]
	v_max_f32_e32 v41, 0, v0
	v_max_f32_e32 v0, v34, v34
	v_pk_mul_f32 v[48:49], v[48:49], v[48:49]
	v_lshl_add_u64 v[46:47], s[8:9], 0, v[46:47]
	v_max_f32_e32 v34, 0, v0
	v_max_f32_e32 v0, v35, v35
	v_cvt_pk_bf16_f32 v43, v48, v49
	v_cvt_pk_bf16_f32 v44, v50, v51
	v_cvt_pk_bf16_f32 v45, v52, v53
	v_lshl_add_u64 v[46:47], v[46:47], 0, v[122:123]
	v_max_f32_e32 v35, 0, v0
	v_max_f32_e32 v0, v36, v36
	global_store_dwordx4 v[46:47], v[42:45], off nt
	v_add_u32_e32 v48, 0xb0, v130
	v_pk_mul_f32 v[38:39], v[38:39], v[38:39]
	v_pk_mul_f32 v[42:43], v[34:35], v[34:35]
	v_max_f32_e32 v34, 0, v0
	v_max_f32_e32 v0, v37, v37
	v_max_f32_e32 v35, 0, v0
	v_max_f32_e32 v0, v30, v30
	v_max_f32_e32 v30, 0, v0
	v_max_f32_e32 v0, v31, v31
	v_max_f32_e32 v31, 0, v0
	v_max_f32_e32 v0, v32, v32
	v_ashrrev_i32_e32 v49, 31, v48
	v_max_f32_e32 v32, 0, v0
	v_max_f32_e32 v0, v33, v33
	v_pk_mul_f32 v[44:45], v[34:35], v[34:35]
	v_cvt_pk_bf16_f32 v34, v38, v39
	v_lshlrev_b64 v[38:39], 14, v[48:49]
	v_max_f32_e32 v33, 0, v0
	v_max_f32_e32 v0, v26, v26
	v_pk_mul_f32 v[40:41], v[40:41], v[40:41]
	v_lshl_add_u64 v[38:39], s[8:9], 0, v[38:39]
	v_max_f32_e32 v26, 0, v0
	v_max_f32_e32 v0, v27, v27
	v_cvt_pk_bf16_f32 v35, v40, v41
	v_cvt_pk_bf16_f32 v36, v42, v43
	v_cvt_pk_bf16_f32 v37, v44, v45
	v_lshl_add_u64 v[38:39], v[38:39], 0, v[122:123]
	v_max_f32_e32 v27, 0, v0
	v_max_f32_e32 v0, v28, v28
	global_store_dwordx4 v[38:39], v[34:37], off nt
	v_pk_mul_f32 v[30:31], v[30:31], v[30:31]
	v_pk_mul_f32 v[32:33], v[32:33], v[32:33]
	v_pk_mul_f32 v[34:35], v[26:27], v[26:27]
	v_max_f32_e32 v26, 0, v0
	v_max_f32_e32 v0, v29, v29
	v_max_f32_e32 v27, 0, v0
	v_max_f32_e32 v0, v22, v22
	v_max_f32_e32 v22, 0, v0
	v_max_f32_e32 v0, v23, v23
	v_max_f32_e32 v23, 0, v0
	v_max_f32_e32 v0, v24, v24
	v_max_f32_e32 v24, 0, v0
	v_max_f32_e32 v0, v25, v25
	v_max_f32_e32 v25, 0, v0
	v_max_f32_e32 v0, v18, v18
	v_pk_mul_f32 v[36:37], v[26:27], v[26:27]
	v_max_f32_e32 v18, 0, v0
	v_max_f32_e32 v0, v19, v19
	v_cvt_pk_bf16_f32 v26, v30, v31
	v_cvt_pk_bf16_f32 v27, v32, v33
	v_cvt_pk_bf16_f32 v28, v34, v35
	v_cvt_pk_bf16_f32 v29, v36, v37
	v_max_f32_e32 v19, 0, v0
	v_max_f32_e32 v0, v20, v20
	global_store_dwordx4 v[62:63], v[26:29], off offset:256 nt
	v_pk_mul_f32 v[22:23], v[22:23], v[22:23]
	v_pk_mul_f32 v[24:25], v[24:25], v[24:25]
	v_pk_mul_f32 v[26:27], v[18:19], v[18:19]
	v_max_f32_e32 v18, 0, v0
	v_max_f32_e32 v0, v21, v21
	v_max_f32_e32 v19, 0, v0
	v_max_f32_e32 v0, v14, v14
	v_max_f32_e32 v14, 0, v0
	v_max_f32_e32 v0, v15, v15
	v_max_f32_e32 v15, 0, v0
	v_max_f32_e32 v0, v16, v16
	v_max_f32_e32 v16, 0, v0
	v_max_f32_e32 v0, v17, v17
	v_max_f32_e32 v17, 0, v0
	v_max_f32_e32 v0, v10, v10
	v_pk_mul_f32 v[28:29], v[18:19], v[18:19]
	v_max_f32_e32 v10, 0, v0
	v_max_f32_e32 v0, v11, v11
	v_cvt_pk_bf16_f32 v18, v22, v23
	v_cvt_pk_bf16_f32 v19, v24, v25
	v_cvt_pk_bf16_f32 v20, v26, v27
	v_cvt_pk_bf16_f32 v21, v28, v29
	v_max_f32_e32 v11, 0, v0
	v_max_f32_e32 v0, v12, v12
	global_store_dwordx4 v[54:55], v[18:21], off offset:256 nt
	v_pk_mul_f32 v[14:15], v[14:15], v[14:15]
	v_pk_mul_f32 v[16:17], v[16:17], v[16:17]
	v_pk_mul_f32 v[18:19], v[10:11], v[10:11]
	v_max_f32_e32 v10, 0, v0
	v_max_f32_e32 v0, v13, v13
	v_max_f32_e32 v11, 0, v0
	v_max_f32_e32 v0, v6, v6
	v_max_f32_e32 v6, 0, v0
	v_max_f32_e32 v0, v7, v7
	v_max_f32_e32 v7, 0, v0
	v_max_f32_e32 v0, v8, v8
	v_max_f32_e32 v8, 0, v0
	v_max_f32_e32 v0, v9, v9
	v_max_f32_e32 v9, 0, v0
	v_max_f32_e32 v0, v2, v2
	v_pk_mul_f32 v[20:21], v[10:11], v[10:11]
	v_max_f32_e32 v2, 0, v0
	v_max_f32_e32 v0, v3, v3
	v_cvt_pk_bf16_f32 v10, v14, v15
	v_cvt_pk_bf16_f32 v11, v16, v17
	v_cvt_pk_bf16_f32 v12, v18, v19
	v_cvt_pk_bf16_f32 v13, v20, v21
	v_max_f32_e32 v3, 0, v0
	v_max_f32_e32 v0, v4, v4
	global_store_dwordx4 v[46:47], v[10:13], off offset:256 nt
	v_pk_mul_f32 v[6:7], v[6:7], v[6:7]
	v_pk_mul_f32 v[8:9], v[8:9], v[8:9]
	v_pk_mul_f32 v[10:11], v[2:3], v[2:3]
	v_max_f32_e32 v2, 0, v0
	v_max_f32_e32 v0, v5, v5
	v_max_f32_e32 v3, 0, v0
	v_pk_mul_f32 v[12:13], v[2:3], v[2:3]
	v_cvt_pk_bf16_f32 v2, v6, v7
	v_cvt_pk_bf16_f32 v3, v8, v9
	v_cvt_pk_bf16_f32 v4, v10, v11
	v_cvt_pk_bf16_f32 v5, v12, v13
	s_and_b64 vcc, exec, s[12:13]
	s_mov_b32 s14, s15
	s_mov_b32 s16, s7
	global_store_dwordx4 v[38:39], v[2:5], off offset:256 nt
	s_cbranch_vccnz .LBB0_83

; DI unsigned pack2(float a, float b) { f32x2_t v = {a, b}; bf16x2_t r = __builtin_convertvector(v, bf16x2_t); return __builtin_bit_cast(unsigned, r); }
; DI void s5_job(const PX& p, int l, int job, unsigned char* smem) {
;     ...
;       if (active && hf == 0) {
; #pragma unroll
;         for (int s = 0; s < 8; s++) {
;           const int st = blk * 8 + s;
;           const int t = dir ? Lseg - 1 - st : st;
;           float q[4];
; #pragma unroll
;           for (int r = 0; r < 4; r++) q[r] = yp[s][r] + exb[(s * 4 + r) * 64];
;           uint2 o;
;           o.x = pack2(q[0], q[1]); o.y = pack2(q[2], q[3]);
;           *(uint2*)(Y + (size_t)(tokbase + t) * 768) = o;
;         }
.LBB0_499:
	s_waitcnt vmcnt(0)
	s_cmp_eq_u32 s12, 0
	s_cbranch_scc1 .Ls5st_nofl
	s_and_saveexec_b64 s[16:17], s[4:5]
	global_store_dwordx2 v[216:217], v[168:169], off
	global_store_dwordx2 v[218:219], v[172:173], off
	global_store_dwordx2 v[220:221], v[176:177], off
	global_store_dwordx2 v[222:223], v[180:181], off
	s_or_b64 exec, exec, s[16:17]

; DI unsigned pack2(float a, float b) { f32x2_t v = {a, b}; bf16x2_t r = __builtin_convertvector(v, bf16x2_t); return __builtin_bit_cast(unsigned, r); }
; DI f32x4 mfma16(bf16x8 a, bf16x8 b, f32x4 c) { return __builtin_amdgcn_mfma_f32_16x16x32_bf16(a, b, c, 0, 0, 0); }
; DI void s5_job(const PX& p, int l, int job, unsigned char* smem) {
;     ...
;           for (int s = 0; s < 8; s++) {
;             const int st = (blk + 1) * 8 + s;
;             const int t = dir ? Lseg - 1 - st : st;
;             unext[s] = *(const uint4*)(Zu + (size_t)(tokbase + t) * 768);
;           }
;         }
; #pragma unroll
;         for (int s = 0; s < 8; s++) {
;           const bf16x8 ub = u4_to_bf8(ucur[s]);
; #pragma unroll
;           for (int tt = 0; tt < 2; tt++) {
;             f32x4 cr, ci;
; #pragma unroll
;             for (int r = 0; r < 4; r++) {
;               cr[r] = lre[tt][r] * sre[tt][r] - lim[tt][r] * sim[tt][r];
;               ci[r] = lre[tt][r] * sim[tt][r] + lim[tt][r] * sre[tt][r];
;             }
;             sre[tt] = mfma16(Are[tt], ub, cr);
;             sim[tt] = mfma16(Aim[tt], ub, ci);
;           }
;           uint4 pr, pi;
;           pr.x = pack2(sre[0][0], sre[0][1]); pr.y = pack2(sre[0][2], sre[0][3]);
;           pr.z = pack2(sre[1][0], sre[1][1]); pr.w = pack2(sre[1][2], sre[1][3]);
;           pi.x = pack2(sim[0][0], sim[0][1]); pi.y = pack2(sim[0][2], sim[0][3]);
;           pi.z = pack2(sim[1][0], sim[1][1]); pi.w = pack2(sim[1][2], sim[1][3]);
;           f32x4 y = f32x4{0.f, 0.f, 0.f, 0.f};
;           y = mfma16(Cf[0], u4_to_bf8(pr), y);
;           y = mfma16(Cf[1], u4_to_bf8(pi), y);
;           yp[s] = y;
;         }
;     ...
;           for (int r = 0; r < 4; r++) q[r] = yp[s][r] + exb[(s * 4 + r) * 64];
;           uint2 o;
;           o.x = pack2(q[0], q[1]); o.y = pack2(q[2], q[3]);
;           *(uint2*)(Y + (size_t)(tokbase + t) * 768) = o;
.LBB0_504:
	s_and_b32 s14, s3, 0x800
	v_lshl_add_u32 v0, s14, 2, v162
	s_cmp_eq_u32 s18, 0
	s_cselect_b32 s23, 1, 0
	s_andn2_b32 s23, s23, s12
	s_and_saveexec_b64 s[14:15], s[4:5]
	s_cbranch_execz .LBB0_510
.LBB0_507:
	v_pk_mul_f32 v[92:93], v[146:147], v[122:123]
	v_pk_mul_f32 v[96:97], v[142:143], v[120:121]
	v_pk_fma_f32 v[94:95], v[144:145], v[118:119], v[92:93] neg_lo:[0,0,1] neg_hi:[0,0,1]
	v_pk_fma_f32 v[92:93], v[140:141], v[116:117], v[96:97] neg_lo:[0,0,1] neg_hi:[0,0,1]
	v_pk_mul_f32 v[100:101], v[144:145], v[122:123]
	v_pk_mul_f32 v[104:105], v[150:151], v[112:113]
	s_waitcnt vmcnt(11)
	v_mfma_f32_16x16x32_bf16 v[96:99], v[12:15], v[40:43], v[92:95]
	s_nop 2
	v_mul_f32_e64 v92, v140, v120
	v_mul_f32_e64 v93, v141, v121
	v_pk_fma_f32 v[94:95], v[146:147], v[118:119], v[100:101]
	v_pk_fma_f32 v[92:93], v[142:143], v[116:117], v[92:93]
	s_nop 1
	v_mfma_f32_16x16x32_bf16 v[100:103], v[16:19], v[40:43], v[92:95]
	s_nop 2
	v_mul_f32_e64 v92, v154, v114
	v_mul_f32_e64 v93, v155, v115
	v_pk_mul_f32 v[114:115], v[152:153], v[114:115]
	v_pk_fma_f32 v[94:95], v[152:153], v[110:111], v[92:93] neg_lo:[0,0,1] neg_hi:[0,0,1]
	v_pk_fma_f32 v[92:93], v[148:149], v[108:109], v[104:105] neg_lo:[0,0,1] neg_hi:[0,0,1]
	v_pk_mul_f32 v[116:117], v[142:143], v[100:101]
	s_nop 0
	v_mfma_f32_16x16x32_bf16 v[104:107], v[4:7], v[40:43], v[92:95]
	s_nop 2
	v_mul_f32_e64 v92, v148, v112
	v_mul_f32_e64 v93, v149, v113
	v_pk_fma_f32 v[94:95], v[154:155], v[110:111], v[114:115]
	v_pk_fma_f32 v[92:93], v[150:151], v[108:109], v[92:93]
	v_cvt_pk_bf16_f32 v112, v100, v101
	v_cvt_pk_bf16_f32 v113, v102, v103
	v_mfma_f32_16x16x32_bf16 v[108:111], v[8:11], v[40:43], v[92:95]
	global_load_dwordx4 v[40:43], v[190:191], off
	v_lshl_add_u64 v[190:191], v[190:191], 0, v[206:207]
	s_cmp_lg_u32 s23, 0
	s_cbranch_scc1 .Ls5st_d0
	global_store_dwordx2 v[216:217], v[168:169], off
	s_branch .Ls5st_e0
.Ls5st_d0:
	global_load_dword v185, v[156:157], off
.Ls5st_e0:
	v_mul_f32_e64 v100, v140, v100
	v_mul_f32_e64 v101, v141, v101
	s_nop 0
	v_cvt_pk_bf16_f32 v92, v96, v97
	v_cvt_pk_bf16_f32 v93, v98, v99
	v_cvt_pk_bf16_f32 v94, v104, v105
	v_cvt_pk_bf16_f32 v95, v106, v107
	s_nop 0
	v_cvt_pk_bf16_f32 v114, v108, v109
	v_cvt_pk_bf16_f32 v115, v110, v111
	v_mfma_f32_16x16x32_bf16 v[92:95], v[20:23], v[92:95], 0
	s_nop 0
	v_mfma_f32_16x16x32_bf16 v[92:95], v[24:27], v[112:115], v[92:95]
	v_mul_f32_e64 v112, v146, v102
	v_mul_f32_e64 v113, v147, v103
	v_pk_mul_f32 v[102:103], v[144:145], v[102:103]
	v_pk_fma_f32 v[114:115], v[144:145], v[98:99], v[112:113] neg_lo:[0,0,1] neg_hi:[0,0,1]
	v_pk_fma_f32 v[112:113], v[140:141], v[96:97], v[116:117] neg_lo:[0,0,1] neg_hi:[0,0,1]
	v_pk_fma_f32 v[98:99], v[146:147], v[98:99], v[102:103]
	v_pk_fma_f32 v[96:97], v[142:143], v[96:97], v[100:101]
	v_pk_mul_f32 v[116:117], v[150:151], v[108:109]
	s_waitcnt vmcnt(11)
	v_mfma_f32_16x16x32_bf16 v[112:115], v[12:15], v[36:39], v[112:115]
	v_mfma_f32_16x16x32_bf16 v[100:103], v[16:19], v[36:39], v[96:99]
	s_nop 2
	v_mul_f32_e64 v96, v154, v110
	v_mul_f32_e64 v97, v155, v111
	v_pk_mul_f32 v[110:111], v[152:153], v[110:111]
	v_pk_fma_f32 v[98:99], v[152:153], v[106:107], v[96:97] neg_lo:[0,0,1] neg_hi:[0,0,1]
	v_pk_fma_f32 v[96:97], v[148:149], v[104:105], v[116:117] neg_lo:[0,0,1] neg_hi:[0,0,1]
	v_pk_mul_f32 v[120:121], v[142:143], v[100:101]
	s_nop 0
	v_mfma_f32_16x16x32_bf16 v[116:119], v[4:7], v[36:39], v[96:99]
	s_nop 2
	v_mul_f32_e64 v96, v148, v108
	v_mul_f32_e64 v97, v149, v109
	v_pk_fma_f32 v[98:99], v[154:155], v[106:107], v[110:111]
	v_pk_fma_f32 v[96:97], v[150:151], v[104:105], v[96:97]
	v_cvt_pk_bf16_f32 v108, v100, v101
	v_cvt_pk_bf16_f32 v109, v102, v103
	v_mfma_f32_16x16x32_bf16 v[104:107], v[8:11], v[36:39], v[96:99]
	global_load_dwordx4 v[36:39], v[192:193], off
	v_lshl_add_u64 v[192:193], v[192:193], 0, v[206:207]
	s_cmp_lg_u32 s23, 0
	s_cbranch_scc1 .Ls5st_d1
	global_store_dwordx2 v[218:219], v[172:173], off
	s_branch .Ls5st_e1

; DI unsigned pack2(float a, float b) { f32x2_t v = {a, b}; bf16x2_t r = __builtin_convertvector(v, bf16x2_t); return __builtin_bit_cast(unsigned, r); }
; DI f32x4 mfma16(bf16x8 a, bf16x8 b, f32x4 c) { return __builtin_amdgcn_mfma_f32_16x16x32_bf16(a, b, c, 0, 0, 0); }
; DI void s5_job(const PX& p, int l, int job, unsigned char* smem) {
;     ...
;           for (int s = 0; s < 8; s++) {
;             const int st = (blk + 1) * 8 + s;
;             const int t = dir ? Lseg - 1 - st : st;
;             unext[s] = *(const uint4*)(Zu + (size_t)(tokbase + t) * 768);
;           }
;         }
; #pragma unroll
;         for (int s = 0; s < 8; s++) {
;           const bf16x8 ub = u4_to_bf8(ucur[s]);
; #pragma unroll
;           for (int tt = 0; tt < 2; tt++) {
;             f32x4 cr, ci;
; #pragma unroll
;             for (int r = 0; r < 4; r++) {
;               cr[r] = lre[tt][r] * sre[tt][r] - lim[tt][r] * sim[tt][r];
;               ci[r] = lre[tt][r] * sim[tt][r] + lim[tt][r] * sre[tt][r];
;             }
;             sre[tt] = mfma16(Are[tt], ub, cr);
;             sim[tt] = mfma16(Aim[tt], ub, ci);
;           }
;           uint4 pr, pi;
;           pr.x = pack2(sre[0][0], sre[0][1]); pr.y = pack2(sre[0][2], sre[0][3]);
;           pr.z = pack2(sre[1][0], sre[1][1]); pr.w = pack2(sre[1][2], sre[1][3]);
;           pi.x = pack2(sim[0][0], sim[0][1]); pi.y = pack2(sim[0][2], sim[0][3]);
;           pi.z = pack2(sim[1][0], sim[1][1]); pi.w = pack2(sim[1][2], sim[1][3]);
;           f32x4 y = f32x4{0.f, 0.f, 0.f, 0.f};
;           y = mfma16(Cf[0], u4_to_bf8(pr), y);
;           y = mfma16(Cf[1], u4_to_bf8(pi), y);
;           yp[s] = y;
;         }
;     ...
;           for (int r = 0; r < 4; r++) q[r] = yp[s][r] + exb[(s * 4 + r) * 64];
;           uint2 o;
;           o.x = pack2(q[0], q[1]); o.y = pack2(q[2], q[3]);
;           *(uint2*)(Y + (size_t)(tokbase + t) * 768) = o;
.Ls5st_e1:
	v_mul_f32_e64 v100, v140, v100
	v_mul_f32_e64 v101, v141, v101
	v_pk_fma_f32 v[100:101], v[142:143], v[112:113], v[100:101]
	v_cvt_pk_bf16_f32 v96, v112, v113
	v_cvt_pk_bf16_f32 v97, v114, v115
	v_cvt_pk_bf16_f32 v98, v116, v117
	v_cvt_pk_bf16_f32 v99, v118, v119
	s_nop 0
	v_cvt_pk_bf16_f32 v110, v104, v105
	v_cvt_pk_bf16_f32 v111, v106, v107
	v_mfma_f32_16x16x32_bf16 v[96:99], v[20:23], v[96:99], 0
	s_nop 0
	v_mfma_f32_16x16x32_bf16 v[96:99], v[24:27], v[108:111], v[96:99]
	v_mul_f32_e64 v108, v146, v102
	v_mul_f32_e64 v109, v147, v103
	v_pk_mul_f32 v[102:103], v[144:145], v[102:103]
	v_pk_fma_f32 v[110:111], v[144:145], v[114:115], v[108:109] neg_lo:[0,0,1] neg_hi:[0,0,1]
	v_pk_fma_f32 v[102:103], v[146:147], v[114:115], v[102:103]
	v_pk_fma_f32 v[108:109], v[140:141], v[112:113], v[120:121] neg_lo:[0,0,1] neg_hi:[0,0,1]
	v_pk_mul_f32 v[120:121], v[150:151], v[104:105]
	s_waitcnt vmcnt(11)
	v_mfma_f32_16x16x32_bf16 v[112:115], v[16:19], v[56:59], v[100:103]
	s_nop 2
	v_mul_f32_e64 v100, v154, v106
	v_mul_f32_e64 v101, v155, v107
	v_mfma_f32_16x16x32_bf16 v[108:111], v[12:15], v[56:59], v[108:111]
	v_fma_f32 v102, v152, v118, -v100
	v_fma_f32 v103, v153, v119, -v101
	v_pk_fma_f32 v[100:101], v[148:149], v[116:117], v[120:121] neg_lo:[0,0,1] neg_hi:[0,0,1]
	v_pk_mul_f32 v[106:107], v[152:153], v[106:107]
	v_pk_mul_f32 v[124:125], v[142:143], v[112:113]
	v_mfma_f32_16x16x32_bf16 v[120:123], v[4:7], v[56:59], v[100:103]
	s_nop 2
	v_mul_f32_e64 v100, v148, v104
	v_mul_f32_e64 v101, v149, v105
	v_pk_fma_f32 v[102:103], v[154:155], v[118:119], v[106:107]
	v_pk_fma_f32 v[100:101], v[150:151], v[116:117], v[100:101]
	v_cvt_pk_bf16_f32 v116, v112, v113
	v_cvt_pk_bf16_f32 v117, v114, v115
	v_mfma_f32_16x16x32_bf16 v[104:107], v[8:11], v[56:59], v[100:103]
	global_load_dwordx4 v[56:59], v[194:195], off
	v_lshl_add_u64 v[194:195], v[194:195], 0, v[206:207]
	s_cmp_lg_u32 s23, 0
	s_cbranch_scc1 .Ls5st_d2
	global_store_dwordx2 v[220:221], v[176:177], off
	s_branch .Ls5st_e2

; DI unsigned pack2(float a, float b) { f32x2_t v = {a, b}; bf16x2_t r = __builtin_convertvector(v, bf16x2_t); return __builtin_bit_cast(unsigned, r); }
; DI f32x4 mfma16(bf16x8 a, bf16x8 b, f32x4 c) { return __builtin_amdgcn_mfma_f32_16x16x32_bf16(a, b, c, 0, 0, 0); }
; DI void s5_job(const PX& p, int l, int job, unsigned char* smem) {
;     ...
;           for (int s = 0; s < 8; s++) {
;             const int st = (blk + 1) * 8 + s;
;             const int t = dir ? Lseg - 1 - st : st;
;             unext[s] = *(const uint4*)(Zu + (size_t)(tokbase + t) * 768);
;           }
;         }
; #pragma unroll
;         for (int s = 0; s < 8; s++) {
;           const bf16x8 ub = u4_to_bf8(ucur[s]);
; #pragma unroll
;           for (int tt = 0; tt < 2; tt++) {
;             f32x4 cr, ci;
; #pragma unroll
;             for (int r = 0; r < 4; r++) {
;               cr[r] = lre[tt][r] * sre[tt][r] - lim[tt][r] * sim[tt][r];
;               ci[r] = lre[tt][r] * sim[tt][r] + lim[tt][r] * sre[tt][r];
;             }
;             sre[tt] = mfma16(Are[tt], ub, cr);
;             sim[tt] = mfma16(Aim[tt], ub, ci);
;           }
;           uint4 pr, pi;
;           pr.x = pack2(sre[0][0], sre[0][1]); pr.y = pack2(sre[0][2], sre[0][3]);
;           pr.z = pack2(sre[1][0], sre[1][1]); pr.w = pack2(sre[1][2], sre[1][3]);
;           pi.x = pack2(sim[0][0], sim[0][1]); pi.y = pack2(sim[0][2], sim[0][3]);
;           pi.z = pack2(sim[1][0], sim[1][1]); pi.w = pack2(sim[1][2], sim[1][3]);
;           f32x4 y = f32x4{0.f, 0.f, 0.f, 0.f};
;           y = mfma16(Cf[0], u4_to_bf8(pr), y);
;           y = mfma16(Cf[1], u4_to_bf8(pi), y);
;           yp[s] = y;
;         }
;     ...
;           for (int r = 0; r < 4; r++) q[r] = yp[s][r] + exb[(s * 4 + r) * 64];
;           uint2 o;
;           o.x = pack2(q[0], q[1]); o.y = pack2(q[2], q[3]);
;           *(uint2*)(Y + (size_t)(tokbase + t) * 768) = o;
.Ls5st_e2:
	v_mul_f32_e64 v112, v140, v112
	v_mul_f32_e64 v113, v141, v113
	s_nop 0
	v_cvt_pk_bf16_f32 v100, v108, v109
	v_cvt_pk_bf16_f32 v101, v110, v111
	v_cvt_pk_bf16_f32 v102, v120, v121
	v_cvt_pk_bf16_f32 v103, v122, v123
	s_nop 0
	v_cvt_pk_bf16_f32 v118, v104, v105
	v_cvt_pk_bf16_f32 v119, v106, v107
	v_mfma_f32_16x16x32_bf16 v[100:103], v[20:23], v[100:103], 0
	s_nop 0
	v_mfma_f32_16x16x32_bf16 v[100:103], v[24:27], v[116:119], v[100:103]
	v_mul_f32_e64 v116, v146, v114
	v_mul_f32_e64 v117, v147, v115
	v_pk_fma_f32 v[118:119], v[144:145], v[110:111], v[116:117] neg_lo:[0,0,1] neg_hi:[0,0,1]
	v_pk_fma_f32 v[116:117], v[140:141], v[108:109], v[124:125] neg_lo:[0,0,1] neg_hi:[0,0,1]
	v_pk_mul_f32 v[124:125], v[144:145], v[114:115]
	v_pk_fma_f32 v[108:109], v[142:143], v[108:109], v[112:113]
	s_waitcnt vmcnt(11)
	v_mfma_f32_16x16x32_bf16 v[114:117], v[12:15], v[52:55], v[116:119]
	v_mul_f32_e64 v112, v154, v106
	v_mul_f32_e64 v113, v155, v107
	v_pk_fma_f32 v[110:111], v[146:147], v[110:111], v[124:125]
	v_pk_fma_f32 v[126:127], v[152:153], v[122:123], v[112:113] neg_lo:[0,0,1] neg_hi:[0,0,1]
	v_pk_mul_f32 v[118:119], v[150:151], v[104:105]
	v_pk_mul_f32 v[106:107], v[152:153], v[106:107]
	v_pk_fma_f32 v[124:125], v[148:149], v[120:121], v[118:119] neg_lo:[0,0,1] neg_hi:[0,0,1]
	v_pk_mul_f32 v[104:105], v[148:149], v[104:105]
	v_pk_fma_f32 v[106:107], v[154:155], v[122:123], v[106:107]
	v_mfma_f32_16x16x32_bf16 v[124:127], v[4:7], v[52:55], v[124:127]
	v_fma_f32 v104, v150, v120, v104
	v_fma_f32 v105, v151, v121, v105
	v_mfma_f32_16x16x32_bf16 v[108:111], v[16:19], v[52:55], v[108:111]
	s_nop 0
	v_mfma_f32_16x16x32_bf16 v[118:121], v[8:11], v[52:55], v[104:107]
	global_load_dwordx4 v[52:55], v[196:197], off
	v_lshl_add_u64 v[196:197], v[196:197], 0, v[206:207]
	s_cmp_lg_u32 s23, 0
	s_cbranch_scc1 .Ls5st_d3
	global_store_dwordx2 v[222:223], v[180:181], off
	s_branch .Ls5st_e3

; DI unsigned pack2(float a, float b) { f32x2_t v = {a, b}; bf16x2_t r = __builtin_convertvector(v, bf16x2_t); return __builtin_bit_cast(unsigned, r); }
; DI f32x4 mfma16(bf16x8 a, bf16x8 b, f32x4 c) { return __builtin_amdgcn_mfma_f32_16x16x32_bf16(a, b, c, 0, 0, 0); }
; DI void s5_job(const PX& p, int l, int job, unsigned char* smem) {
;     ...
;           for (int s = 0; s < 8; s++) {
;             const int st = (blk + 1) * 8 + s;
;             const int t = dir ? Lseg - 1 - st : st;
;             unext[s] = *(const uint4*)(Zu + (size_t)(tokbase + t) * 768);
;           }
;         }
; #pragma unroll
;         for (int s = 0; s < 8; s++) {
;           const bf16x8 ub = u4_to_bf8(ucur[s]);
; #pragma unroll
;           for (int tt = 0; tt < 2; tt++) {
;             f32x4 cr, ci;
; #pragma unroll
;             for (int r = 0; r < 4; r++) {
;               cr[r] = lre[tt][r] * sre[tt][r] - lim[tt][r] * sim[tt][r];
;               ci[r] = lre[tt][r] * sim[tt][r] + lim[tt][r] * sre[tt][r];
;             }
;             sre[tt] = mfma16(Are[tt], ub, cr);
;             sim[tt] = mfma16(Aim[tt], ub, ci);
;           }
;           uint4 pr, pi;
;           pr.x = pack2(sre[0][0], sre[0][1]); pr.y = pack2(sre[0][2], sre[0][3]);
;           pr.z = pack2(sre[1][0], sre[1][1]); pr.w = pack2(sre[1][2], sre[1][3]);
;           pi.x = pack2(sim[0][0], sim[0][1]); pi.y = pack2(sim[0][2], sim[0][3]);
;           pi.z = pack2(sim[1][0], sim[1][1]); pi.w = pack2(sim[1][2], sim[1][3]);
;           f32x4 y = f32x4{0.f, 0.f, 0.f, 0.f};
;           y = mfma16(Cf[0], u4_to_bf8(pr), y);
;           y = mfma16(Cf[1], u4_to_bf8(pi), y);
;           yp[s] = y;
;         }
.Ls5st_e3:
	s_nop 2
	v_cvt_pk_bf16_f32 v104, v114, v115
	v_cvt_pk_bf16_f32 v105, v116, v117
	v_cvt_pk_bf16_f32 v106, v124, v125
	v_cvt_pk_bf16_f32 v107, v126, v127
	v_cvt_pk_bf16_f32 v128, v108, v109
	v_cvt_pk_bf16_f32 v129, v110, v111
	v_mfma_f32_16x16x32_bf16 v[104:107], v[20:23], v[104:107], 0
	v_cvt_pk_bf16_f32 v130, v118, v119
	v_cvt_pk_bf16_f32 v131, v120, v121
	v_pk_mul_f32 v[122:123], v[142:143], v[108:109]
	v_pk_mul_f32 v[112:113], v[146:147], v[110:111]
	v_mfma_f32_16x16x32_bf16 v[104:107], v[24:27], v[128:131], v[104:107]
	v_fma_f32 v128, v140, v114, -v122
	v_fma_f32 v129, v141, v115, -v123
	v_pk_mul_f32 v[122:123], v[144:145], v[110:111]
	v_pk_mul_f32 v[108:109], v[140:141], v[108:109]
	v_pk_fma_f32 v[130:131], v[144:145], v[116:117], v[112:113] neg_lo:[0,0,1] neg_hi:[0,0,1]
	v_pk_fma_f32 v[116:117], v[146:147], v[116:117], v[122:123]
	v_pk_fma_f32 v[114:115], v[142:143], v[114:115], v[108:109]
	v_pk_mul_f32 v[108:109], v[154:155], v[120:121]
	v_pk_mul_f32 v[122:123], v[150:151], v[118:119]
	s_waitcnt vmcnt(11)
	v_mfma_f32_16x16x32_bf16 v[110:113], v[12:15], v[72:75], v[128:131]
	v_mul_f32_e64 v118, v148, v118
	v_mul_f32_e64 v119, v149, v119
	s_nop 0
	v_pk_fma_f32 v[130:131], v[152:153], v[126:127], v[108:109] neg_lo:[0,0,1] neg_hi:[0,0,1]
	v_pk_fma_f32 v[128:129], v[148:149], v[124:125], v[122:123] neg_lo:[0,0,1] neg_hi:[0,0,1]
	v_pk_mul_f32 v[108:109], v[152:153], v[120:121]
	v_pk_fma_f32 v[124:125], v[150:151], v[124:125], v[118:119]
	v_mfma_f32_16x16x32_bf16 v[120:123], v[4:7], v[72:75], v[128:131]
	v_fma_f32 v126, v154, v126, v108
	v_fma_f32 v127, v155, v127, v109
	v_mfma_f32_16x16x32_bf16 v[114:117], v[16:19], v[72:75], v[114:117]
	s_nop 0
	v_mfma_f32_16x16x32_bf16 v[128:131], v[8:11], v[72:75], v[124:127]
	global_load_dwordx4 v[72:75], v[198:199], off
	v_lshl_add_u64 v[198:199], v[198:199], 0, v[206:207]
	s_nop 2
	v_cvt_pk_bf16_f32 v124, v110, v111
	v_cvt_pk_bf16_f32 v125, v112, v113
	v_cvt_pk_bf16_f32 v126, v120, v121
	v_cvt_pk_bf16_f32 v127, v122, v123
	v_cvt_pk_bf16_f32 v132, v114, v115
	v_cvt_pk_bf16_f32 v133, v116, v117
	v_mfma_f32_16x16x32_bf16 v[124:127], v[20:23], v[124:127], 0
	v_cvt_pk_bf16_f32 v134, v128, v129
	v_cvt_pk_bf16_f32 v135, v130, v131
	v_pk_mul_f32 v[108:109], v[146:147], v[116:117]
	v_pk_mul_f32 v[118:119], v[142:143], v[114:115]
	v_mfma_f32_16x16x32_bf16 v[124:127], v[24:27], v[132:135], v[124:127]
	v_fma_f32 v134, v144, v112, -v108
	v_fma_f32 v135, v145, v113, -v109
	v_pk_mul_f32 v[108:109], v[144:145], v[116:117]
	v_pk_mul_f32 v[114:115], v[140:141], v[114:115]
	v_pk_fma_f32 v[132:133], v[140:141], v[110:111], v[118:119] neg_lo:[0,0,1] neg_hi:[0,0,1]
	v_pk_fma_f32 v[112:113], v[146:147], v[112:113], v[108:109]
	v_pk_fma_f32 v[110:111], v[142:143], v[110:111], v[114:115]
	s_waitcnt vmcnt(11)
	v_mfma_f32_16x16x32_bf16 v[116:119], v[12:15], v[68:71], v[132:135]
	v_mfma_f32_16x16x32_bf16 v[108:111], v[16:19], v[68:71], v[110:113]
	s_nop 1
	v_mul_f32_e64 v132, v150, v128
	v_mul_f32_e64 v133, v151, v129
	v_pk_mul_f32 v[128:129], v[148:149], v[128:129]
	v_pk_mul_f32 v[112:113], v[154:155], v[130:131]
	v_pk_mul_f32 v[130:131], v[152:153], v[130:131]
	v_pk_fma_f32 v[114:115], v[152:153], v[122:123], v[112:113] neg_lo:[0,0,1] neg_hi:[0,0,1]
	v_pk_fma_f32 v[112:113], v[148:149], v[120:121], v[132:133] neg_lo:[0,0,1] neg_hi:[0,0,1]
	v_pk_fma_f32 v[122:123], v[154:155], v[122:123], v[130:131]
	v_pk_fma_f32 v[120:121], v[150:151], v[120:121], v[128:129]
	v_mfma_f32_16x16x32_bf16 v[112:115], v[4:7], v[68:71], v[112:115]
	v_cvt_pk_bf16_f32 v128, v116, v117
	v_cvt_pk_bf16_f32 v129, v118, v119
	v_cvt_pk_bf16_f32 v132, v108, v109
	v_mfma_f32_16x16x32_bf16 v[120:123], v[8:11], v[68:71], v[120:123]
	global_load_dwordx4 v[68:71], v[200:201], off
	v_lshl_add_u64 v[200:201], v[200:201], 0, v[206:207]
	v_cvt_pk_bf16_f32 v133, v110, v111
	s_nop 2
	v_cvt_pk_bf16_f32 v130, v112, v113
	v_cvt_pk_bf16_f32 v131, v114, v115
	v_pk_mul_f32 v[136:137], v[142:143], v[108:109]
	v_pk_mul_f32 v[108:109], v[140:141], v[108:109]
	v_mfma_f32_16x16x32_bf16 v[128:131], v[20:23], v[128:131], 0
	v_cvt_pk_bf16_f32 v134, v120, v121
	v_cvt_pk_bf16_f32 v135, v122, v123
	v_pk_fma_f32 v[108:109], v[142:143], v[116:117], v[108:109]
	s_nop 0
	v_mfma_f32_16x16x32_bf16 v[128:131], v[24:27], v[132:135], v[128:131]
	v_mul_f32_e64 v132, v146, v110
	v_mul_f32_e64 v133, v147, v111
	v_pk_mul_f32 v[110:111], v[144:145], v[110:111]
	v_pk_fma_f32 v[134:135], v[144:145], v[118:119], v[132:133] neg_lo:[0,0,1] neg_hi:[0,0,1]
	v_pk_fma_f32 v[132:133], v[140:141], v[116:117], v[136:137] neg_lo:[0,0,1] neg_hi:[0,0,1]
	v_pk_mul_f32 v[116:117], v[154:155], v[122:123]
	v_pk_fma_f32 v[110:111], v[146:147], v[118:119], v[110:111]
	s_waitcnt vmcnt(11)
; DI unsigned pack2(float a, float b) { f32x2_t v = {a, b}; bf16x2_t r = __builtin_convertvector(v, bf16x2_t); return __builtin_bit_cast(unsigned, r); }
; DI f32x4 mfma16(bf16x8 a, bf16x8 b, f32x4 c) { return __builtin_amdgcn_mfma_f32_16x16x32_bf16(a, b, c, 0, 0, 0); }
; DI void s5_job(const PX& p, int l, int job, unsigned char* smem) {
;     ...
;           for (int s = 0; s < 8; s++) {
;             const int st = (blk + 1) * 8 + s;
;             const int t = dir ? Lseg - 1 - st : st;
;             unext[s] = *(const uint4*)(Zu + (size_t)(tokbase + t) * 768);
;           }
;         }
; #pragma unroll
;         for (int s = 0; s < 8; s++) {
;           const bf16x8 ub = u4_to_bf8(ucur[s]);
; #pragma unroll
;           for (int tt = 0; tt < 2; tt++) {
;             f32x4 cr, ci;
; #pragma unroll
;             for (int r = 0; r < 4; r++) {
;               cr[r] = lre[tt][r] * sre[tt][r] - lim[tt][r] * sim[tt][r];
;               ci[r] = lre[tt][r] * sim[tt][r] + lim[tt][r] * sre[tt][r];
;             }
;             sre[tt] = mfma16(Are[tt], ub, cr);
;             sim[tt] = mfma16(Aim[tt], ub, ci);
;           }
;           uint4 pr, pi;
;           pr.x = pack2(sre[0][0], sre[0][1]); pr.y = pack2(sre[0][2], sre[0][3]);
;           pr.z = pack2(sre[1][0], sre[1][1]); pr.w = pack2(sre[1][2], sre[1][3]);
;           pi.x = pack2(sim[0][0], sim[0][1]); pi.y = pack2(sim[0][2], sim[0][3]);
;           pi.z = pack2(sim[1][0], sim[1][1]); pi.w = pack2(sim[1][2], sim[1][3]);
;           f32x4 y = f32x4{0.f, 0.f, 0.f, 0.f};
;           y = mfma16(Cf[0], u4_to_bf8(pr), y);
;           y = mfma16(Cf[1], u4_to_bf8(pi), y);
;           yp[s] = y;
;         }
;         if (hf == 1) {
; #pragma unroll
;           for (int s = 0; s < 8; s++)
; #pragma unroll
;             for (int r = 0; r < 4; r++) exb[(s * 4 + r) * 64] = yp[s][r];
;         }
	v_mfma_f32_16x16x32_bf16 v[136:139], v[12:15], v[88:91], v[132:135]
	v_fma_f32 v118, v152, v114, -v116
	v_fma_f32 v119, v153, v115, -v117
	v_pk_mul_f32 v[122:123], v[152:153], v[122:123]
	v_pk_mul_f32 v[132:133], v[150:151], v[120:121]
	v_pk_fma_f32 v[114:115], v[154:155], v[114:115], v[122:123]
	v_pk_fma_f32 v[116:117], v[148:149], v[112:113], v[132:133] neg_lo:[0,0,1] neg_hi:[0,0,1]
	v_mfma_f32_16x16x32_bf16 v[108:111], v[16:19], v[88:91], v[108:111]
	s_nop 0
	v_mfma_f32_16x16x32_bf16 v[164:167], v[4:7], v[88:91], v[116:119]
	s_nop 2
	v_mul_f32_e64 v116, v148, v120
	v_mul_f32_e64 v117, v149, v121
	s_nop 0
	v_cvt_pk_bf16_f32 v120, v108, v109
	v_pk_fma_f32 v[112:113], v[150:151], v[112:113], v[116:117]
	v_cvt_pk_bf16_f32 v116, v136, v137
	v_cvt_pk_bf16_f32 v117, v138, v139
	v_mfma_f32_16x16x32_bf16 v[112:115], v[8:11], v[88:91], v[112:115]
	global_load_dwordx4 v[88:91], v[202:203], off
	v_lshl_add_u64 v[202:203], v[202:203], 0, v[206:207]
	v_cvt_pk_bf16_f32 v118, v164, v165
	v_cvt_pk_bf16_f32 v119, v166, v167
	v_cvt_pk_bf16_f32 v121, v110, v111
	s_nop 0
	v_mfma_f32_16x16x32_bf16 v[116:119], v[20:23], v[116:119], 0
	s_nop 2
	v_cvt_pk_bf16_f32 v122, v112, v113
	v_cvt_pk_bf16_f32 v123, v114, v115
	s_nop 1
	v_mfma_f32_16x16x32_bf16 v[132:135], v[24:27], v[120:123], v[116:119]
	v_mul_f32_e64 v120, v142, v108
	v_mul_f32_e64 v121, v143, v109
	v_pk_mul_f32 v[108:109], v[140:141], v[108:109]
	v_pk_mul_f32 v[116:117], v[146:147], v[110:111]
	v_pk_mul_f32 v[110:111], v[144:145], v[110:111]
	v_pk_fma_f32 v[108:109], v[142:143], v[136:137], v[108:109]
	v_pk_fma_f32 v[110:111], v[146:147], v[138:139], v[110:111]
	v_pk_fma_f32 v[118:119], v[144:145], v[138:139], v[116:117] neg_lo:[0,0,1] neg_hi:[0,0,1]
	v_pk_fma_f32 v[116:117], v[140:141], v[136:137], v[120:121] neg_lo:[0,0,1] neg_hi:[0,0,1]
	s_waitcnt vmcnt(11)
	v_mfma_f32_16x16x32_bf16 v[120:123], v[16:19], v[84:87], v[108:111]
	v_mul_f32_e64 v136, v150, v112
	v_mul_f32_e64 v137, v151, v113
	v_pk_mul_f32 v[112:113], v[148:149], v[112:113]
	v_pk_mul_f32 v[108:109], v[154:155], v[114:115]
	v_mfma_f32_16x16x32_bf16 v[116:119], v[12:15], v[84:87], v[116:119]
	v_fma_f32 v110, v152, v166, -v108
	v_fma_f32 v111, v153, v167, -v109
	v_pk_fma_f32 v[108:109], v[148:149], v[164:165], v[136:137] neg_lo:[0,0,1] neg_hi:[0,0,1]
	v_pk_mul_f32 v[114:115], v[152:153], v[114:115]
	v_pk_fma_f32 v[112:113], v[150:151], v[164:165], v[112:113]
	v_mfma_f32_16x16x32_bf16 v[108:111], v[4:7], v[84:87], v[108:111]
	v_fma_f32 v114, v154, v166, v114
	v_fma_f32 v115, v155, v167, v115
	v_cvt_pk_bf16_f32 v136, v116, v117
	v_cvt_pk_bf16_f32 v137, v118, v119
	v_mfma_f32_16x16x32_bf16 v[112:115], v[8:11], v[84:87], v[112:115]
	global_load_dwordx4 v[84:87], v[204:205], off
	v_lshl_add_u64 v[204:205], v[204:205], 0, v[206:207]
	v_cvt_pk_bf16_f32 v164, v120, v121
	s_nop 1
	v_cvt_pk_bf16_f32 v138, v108, v109
	v_cvt_pk_bf16_f32 v139, v110, v111
	v_cvt_pk_bf16_f32 v165, v122, v123
	s_nop 0
	v_mfma_f32_16x16x32_bf16 v[136:139], v[20:23], v[136:139], 0
	v_cvt_pk_bf16_f32 v166, v112, v113
	v_cvt_pk_bf16_f32 v167, v114, v115
	s_nop 1
	v_mfma_f32_16x16x32_bf16 v[136:139], v[24:27], v[164:167], v[136:139]
	v_mad_u32_u24 v163, v211, 12, v0
	s_and_saveexec_b64 s[16:17], s[8:9]
	s_cbranch_execz .Ls5x_w0
	ds_write_b128 v163, v[92:95]
	ds_write_b128 v163, v[96:99] offset:1024
	ds_write_b128 v163, v[100:103] offset:2048
	ds_write_b128 v163, v[104:107] offset:3072

; DI unsigned pack2(float a, float b) { f32x2_t v = {a, b}; bf16x2_t r = __builtin_convertvector(v, bf16x2_t); return __builtin_bit_cast(unsigned, r); }
; DI void s5_job(const PX& p, int l, int job, unsigned char* smem) {
;     ...
;       __syncthreads();
;       if (active && hf == 0) {
; #pragma unroll
;         for (int s = 0; s < 8; s++) {
;           const int st = blk * 8 + s;
;           const int t = dir ? Lseg - 1 - st : st;
;           float q[4];
; #pragma unroll
;           for (int r = 0; r < 4; r++) q[r] = yp[s][r] + exb[(s * 4 + r) * 64];
;           uint2 o;
;           o.x = pack2(q[0], q[1]); o.y = pack2(q[2], q[3]);
;           *(uint2*)(Y + (size_t)(tokbase + t) * 768) = o;
;         }
;       }
.LBB0_510:
	s_or_b64 exec, exec, s[14:15]
	s_waitcnt lgkmcnt(0)
	s_barrier
	s_and_saveexec_b64 s[14:15], s[10:11]
	s_cbranch_execz .Ls5x_r0
	ds_read_b128 v[168:171], v163
	ds_read_b128 v[172:175], v163 offset:1024
	ds_read_b128 v[176:179], v163 offset:2048
	ds_read_b128 v[180:183], v163 offset:3072
	s_add_i32 s16, s20, -15
	s_add_i32 s21, s19, 8
	s_mov_b32 s17, s16
	v_mov_b32_e32 v3, s21
	v_mov_b32_e32 v184, s17
	v_cndmask_b32_e64 v3, v3, v184, s[6:7]
	v_add_u32_e32 v3, v3, v2
	v_mad_i64_i32 v[216:217], s[22:23], v3, s81, v[158:159]
	s_waitcnt lgkmcnt(3)
	v_pk_add_f32 v[168:169], v[92:93], v[168:169]
	v_pk_add_f32 v[170:171], v[94:95], v[170:171]
	v_cvt_pk_bf16_f32 v168, v168, v169
	v_cvt_pk_bf16_f32 v169, v170, v171
	s_xor_b32 s21, s16, -2
	s_add_i32 s17, s20, -14
	s_add_i32 s21, s21, s1
	v_mov_b32_e32 v3, s21
	v_mov_b32_e32 v184, s17
	v_cndmask_b32_e64 v3, v3, v184, s[6:7]
	v_add_u32_e32 v3, v3, v2
	v_mad_i64_i32 v[218:219], s[22:23], v3, s81, v[158:159]
	s_waitcnt lgkmcnt(2)
	v_pk_add_f32 v[172:173], v[96:97], v[172:173]
	v_pk_add_f32 v[174:175], v[98:99], v[174:175]
	v_cvt_pk_bf16_f32 v172, v172, v173
	v_cvt_pk_bf16_f32 v173, v174, v175
	s_xor_b32 s21, s16, -3
	s_add_i32 s17, s20, -13
	s_add_i32 s21, s21, s1
	v_mov_b32_e32 v3, s21
	v_mov_b32_e32 v184, s17
	v_cndmask_b32_e64 v3, v3, v184, s[6:7]
	v_add_u32_e32 v3, v3, v2
	v_mad_i64_i32 v[220:221], s[22:23], v3, s81, v[158:159]
	s_waitcnt lgkmcnt(1)
	v_pk_add_f32 v[176:177], v[100:101], v[176:177]
	v_pk_add_f32 v[178:179], v[102:103], v[178:179]
	v_cvt_pk_bf16_f32 v176, v176, v177
	v_cvt_pk_bf16_f32 v177, v178, v179
	s_xor_b32 s21, s16, -4
	s_add_i32 s17, s20, -12
	s_add_i32 s21, s21, s1
	v_mov_b32_e32 v3, s21
	v_mov_b32_e32 v184, s17
	v_cndmask_b32_e64 v3, v3, v184, s[6:7]
	v_add_u32_e32 v3, v3, v2
	v_mad_i64_i32 v[222:223], s[22:23], v3, s81, v[158:159]
	s_waitcnt lgkmcnt(0)
	v_pk_add_f32 v[180:181], v[104:105], v[180:181]
	v_pk_add_f32 v[182:183], v[106:107], v[182:183]
	v_cvt_pk_bf16_f32 v180, v180, v181
	v_cvt_pk_bf16_f32 v181, v182, v183
.Ls5x_r0:
	s_or_b64 exec, exec, s[14:15]
	s_and_b64 s[16:17], s[4:5], s[8:9]
	s_and_saveexec_b64 s[14:15], s[16:17]
	s_cbranch_execz .Ls5x_r1
	ds_read_b128 v[168:171], v163 offset:4096
	ds_read_b128 v[172:175], v163 offset:5120
	ds_read_b128 v[176:179], v163 offset:6144
	ds_read_b128 v[180:183], v163 offset:7168
	s_add_i32 s16, s20, -15
	s_xor_b32 s21, s16, -5
	s_add_i32 s17, s20, -11
	s_add_i32 s21, s21, s1
	v_mov_b32_e32 v3, s21
	v_mov_b32_e32 v184, s17
	v_cndmask_b32_e64 v3, v3, v184, s[6:7]
	v_add_u32_e32 v3, v3, v2
	v_mad_i64_i32 v[216:217], s[22:23], v3, s81, v[158:159]
	s_waitcnt lgkmcnt(3)
	v_pk_add_f32 v[168:169], v[124:125], v[168:169]
	v_pk_add_f32 v[170:171], v[126:127], v[170:171]
	v_cvt_pk_bf16_f32 v168, v168, v169
	v_cvt_pk_bf16_f32 v169, v170, v171
	s_xor_b32 s21, s16, -6
	s_add_i32 s17, s20, -10
	s_add_i32 s21, s21, s1
	v_mov_b32_e32 v3, s21
	v_mov_b32_e32 v184, s17
	v_cndmask_b32_e64 v3, v3, v184, s[6:7]
	v_add_u32_e32 v3, v3, v2
	v_mad_i64_i32 v[218:219], s[22:23], v3, s81, v[158:159]
	s_waitcnt lgkmcnt(2)
	v_pk_add_f32 v[172:173], v[128:129], v[172:173]
	v_pk_add_f32 v[174:175], v[130:131], v[174:175]
	v_cvt_pk_bf16_f32 v172, v172, v173
	v_cvt_pk_bf16_f32 v173, v174, v175
	s_xor_b32 s21, s16, -7
	s_add_i32 s17, s20, -9
	s_add_i32 s21, s21, s1
	v_mov_b32_e32 v3, s21
	v_mov_b32_e32 v184, s17
	v_cndmask_b32_e64 v3, v3, v184, s[6:7]
	v_add_u32_e32 v3, v3, v2
	v_mad_i64_i32 v[220:221], s[22:23], v3, s81, v[158:159]
	s_waitcnt lgkmcnt(1)
	v_pk_add_f32 v[176:177], v[132:133], v[176:177]
	v_pk_add_f32 v[178:179], v[134:135], v[178:179]
	v_cvt_pk_bf16_f32 v176, v176, v177
	v_cvt_pk_bf16_f32 v177, v178, v179
	s_xor_b32 s21, s16, -8
	s_add_i32 s17, s20, -8
	s_add_i32 s21, s21, s1
	v_mov_b32_e32 v3, s21
	v_mov_b32_e32 v184, s17
	v_cndmask_b32_e64 v3, v3, v184, s[6:7]
	v_add_u32_e32 v3, v3, v2
	v_mad_i64_i32 v[222:223], s[22:23], v3, s81, v[158:159]
	s_waitcnt lgkmcnt(0)
	v_pk_add_f32 v[180:181], v[136:137], v[180:181]
	v_pk_add_f32 v[182:183], v[138:139], v[182:183]
	v_cvt_pk_bf16_f32 v180, v180, v181
	v_cvt_pk_bf16_f32 v181, v182, v183

; DI float sin_f(float x) { float s_, c_; sincos_f(x, s_, c_); return s_; }
; DI void filter_item(const PX& p, int it, float* sm) {
;     ...
;   {
;     float s = p.in[12][l * 64 + i];
;     const float* w2 = p.in[11] + (size_t)l * 64 * 64;
; #pragma unroll 16
;     for (int k = 0; k < 64; k++) s += h1[lg * 64 + k] * w2[k * 64 + i];
;     h2[lg * 64 + i] = sin_f(fr * s);
;   }
;   __syncthreads();
;   const float* w3 = p.in[13] + (size_t)l * 64 * 3072;
;   float sacc[6][8];
; #pragma unroll
;   for (int q6 = 0; q6 < 6; q6++)
; #pragma unroll
;     for (int q = 0; q < 8; q++) sacc[q6][q] = 0.f;
; #pragma unroll 4
;   for (int k = 0; k < 64; k++) {
;     float wv[6];
; #pragma unroll
;     for (int q6 = 0; q6 < 6; q6++) wv[q6] = w3[k * 3072 + tid + NTHR * q6];
.LBB0_877:
	v_lshl_add_u64 v[8:9], v[2:3], 0, s[4:5]
	global_load_dword v7, v[8:9], off
	global_load_dword v24, v[8:9], off offset:256
	global_load_dword v25, v[8:9], off offset:512
	global_load_dword v26, v[8:9], off offset:768
	global_load_dword v27, v[8:9], off offset:1024
	global_load_dword v28, v[8:9], off offset:1280
	global_load_dword v29, v[8:9], off offset:1536
	global_load_dword v30, v[8:9], off offset:1792
	global_load_dword v31, v[8:9], off offset:2048
	global_load_dword v32, v[8:9], off offset:2304
	global_load_dword v33, v[8:9], off offset:2560
	global_load_dword v34, v[8:9], off offset:2816
	global_load_dword v35, v[8:9], off offset:3072
	global_load_dword v36, v[8:9], off offset:3328
	global_load_dword v37, v[8:9], off offset:3584
	global_load_dword v38, v[8:9], off offset:3840
	ds_read_b128 v[8:11], v5
	ds_read_b128 v[12:15], v5 offset:16
	ds_read_b128 v[16:19], v5 offset:32
	ds_read_b128 v[20:23], v5 offset:48
	s_add_u32 s4, s4, 0x1000
	s_addc_u32 s5, s5, 0
	v_add_u32_e32 v5, 64, v5
	s_cmpk_eq_i32 s4, 0x4000
	s_waitcnt vmcnt(15) lgkmcnt(3)
	v_fmac_f32_e32 v0, v8, v7
	s_waitcnt vmcnt(14)
	v_fmac_f32_e32 v0, v9, v24
	s_waitcnt vmcnt(13)
	v_fmac_f32_e32 v0, v10, v25
	s_waitcnt vmcnt(12)
	v_fmac_f32_e32 v0, v11, v26
	s_waitcnt vmcnt(11) lgkmcnt(2)
	v_fmac_f32_e32 v0, v12, v27
	s_waitcnt vmcnt(10)
	v_fmac_f32_e32 v0, v13, v28
	s_waitcnt vmcnt(9)
	v_fmac_f32_e32 v0, v14, v29
	s_waitcnt vmcnt(8)
	v_fmac_f32_e32 v0, v15, v30
	s_waitcnt vmcnt(7) lgkmcnt(1)
	v_fmac_f32_e32 v0, v16, v31
	s_waitcnt vmcnt(6)
	v_fmac_f32_e32 v0, v17, v32
	s_waitcnt vmcnt(5)
	v_fmac_f32_e32 v0, v18, v33
	s_waitcnt vmcnt(4)
	v_fmac_f32_e32 v0, v19, v34
	s_waitcnt vmcnt(3) lgkmcnt(0)
	v_fmac_f32_e32 v0, v20, v35
	s_waitcnt vmcnt(2)
	v_fmac_f32_e32 v0, v21, v36
	s_waitcnt vmcnt(1)
	v_fmac_f32_e32 v0, v22, v37
	s_waitcnt vmcnt(0)
	v_fmac_f32_e32 v0, v23, v38
	s_cbranch_scc0 .LBB0_877
	v_mul_f32_e32 v5, v6, v0
	v_mul_f32_e32 v0, 0x3f22f983, v5
	v_rndne_f32_e32 v0, v0
	v_fmac_f32_e32 v5, 0xbfc90000, v0
	v_fmac_f32_e32 v5, 0xb9fda000, v0
	v_fmac_f32_e32 v5, 0xb3a22169, v0
	v_cvt_i32_f32_e32 v6, v0
	v_mul_f32_e32 v0, v5, v5
	v_mov_b32_e32 v3, 0x3c08839e
	v_fmamk_f32 v3, v0, 0xb94ca1f9, v3
	v_mul_f32_e32 v2, v5, v0
	v_fmaak_f32 v3, v0, v3, 0xbe2aaaa3
	v_fmac_f32_e32 v5, v2, v3
	v_mov_b32_e32 v2, 0xbab6061a
	v_fmamk_f32 v187, v0, 0x37ccf5ce, v2
	v_pk_mul_f32 v[2:3], v[0:1], v[186:187] op_sel_hi:[0,1]
	v_mul_f32_e32 v7, v0, v0
	v_add_f32_e32 v0, 0x3d2aaaa5, v3
	v_sub_f32_e32 v2, 1.0, v2
	v_fmac_f32_e32 v2, v7, v0
	v_and_b32_e32 v0, 1, v6
	v_cmp_eq_u32_e32 vcc, 0, v0
	v_readlane_b32 s4, v253, 31
	v_readlane_b32 s8, v252, 19
	v_cndmask_b32_e32 v0, v2, v5, vcc
	v_and_b32_e32 v2, 2, v6
	v_cmp_eq_u32_e32 vcc, 0, v2
	s_mul_i32 s4, s4, 0xc0000
	v_readlane_b32 s18, v252, 29
	v_cndmask_b32_e64 v0, -v0, v0, vcc
	v_readlane_b32 s5, v253, 32
	v_readlane_b32 s9, v252, 20
	v_readlane_b32 s10, v252, 21
	v_readlane_b32 s19, v252, 30
	s_add_u32 s4, s18, s4
	v_mov_b32_e32 v8, 0
	s_mov_b32 s0, 0
	ds_write_b32 v4, v0 offset:3328
	s_addc_u32 s5, s19, 0
	s_movk_i32 s8, 0xd00
	v_mov_b32_e32 v9, v8
	v_mov_b32_e32 v10, v8
	v_mov_b32_e32 v11, v8
	v_mov_b32_e32 v12, v8
	v_mov_b32_e32 v13, v8
	v_mov_b32_e32 v14, v8
	v_mov_b32_e32 v15, v8
	v_mov_b32_e32 v16, v8
	v_mov_b32_e32 v17, v8
	v_mov_b32_e32 v18, v8
	v_mov_b32_e32 v19, v8
	v_mov_b32_e32 v20, v8
	v_mov_b32_e32 v21, v8
	v_mov_b32_e32 v22, v8
	v_mov_b32_e32 v23, v8
	v_mov_b32_e32 v24, v8
	v_mov_b32_e32 v25, v8
	v_mov_b32_e32 v26, v8
	v_mov_b32_e32 v27, v8
	v_mov_b32_e32 v28, v8
	v_mov_b32_e32 v29, v8
	v_mov_b32_e32 v30, v8
	v_mov_b32_e32 v31, v8
	v_mov_b32_e32 v32, v8
	v_mov_b32_e32 v33, v8
	v_mov_b32_e32 v34, v8
	v_mov_b32_e32 v35, v8
	v_mov_b32_e32 v36, v8
	v_mov_b32_e32 v37, v8
	v_mov_b32_e32 v38, v8
	v_mov_b32_e32 v39, v8
	v_mov_b32_e32 v40, v8
	v_mov_b32_e32 v41, v8
	v_mov_b32_e32 v42, v8
	v_mov_b32_e32 v43, v8
	v_mov_b32_e32 v44, v8
	v_mov_b32_e32 v45, v8
	v_mov_b32_e32 v46, v8
	v_mov_b32_e32 v47, v8
	v_mov_b32_e32 v48, v8
	v_mov_b32_e32 v49, v8
	v_mov_b32_e32 v6, v8
	v_mov_b32_e32 v7, v8
	v_mov_b32_e32 v4, v8
	v_mov_b32_e32 v5, v8
	v_mov_b32_e32 v2, v8
	v_mov_b32_e32 v3, v8
	s_movk_i32 s9, 0x1000
	s_movk_i32 s10, 0x2000
	s_waitcnt lgkmcnt(0)
	s_barrier
	v_readlane_b32 s11, v252, 22
	v_readlane_b32 s12, v252, 23
	v_readlane_b32 s13, v252, 24
	v_readlane_b32 s14, v252, 25
	v_readlane_b32 s15, v252, 26
	v_readlane_b32 s16, v252, 27
	v_readlane_b32 s17, v252, 28
	v_readlane_b32 s20, v252, 31
	v_readlane_b32 s21, v252, 32
	v_readlane_b32 s22, v252, 33
	v_readlane_b32 s23, v252, 34
	s_waitcnt vmcnt(0)
	v_lshlrev_b32_e32 v88, 2, v54
	v_mov_b32_e32 v89, 0
	v_lshl_add_u64 v[88:89], s[4:5], 0, v[88:89]
	v_mov_b32_e32 v94, 0x1000
	v_mov_b32_e32 v95, 0
	v_lshl_add_u64 v[90:91], v[88:89], 0, v[94:95]
	v_lshl_add_u64 v[92:93], v[90:91], 0, v[94:95]
	s_mov_b64 s[4:5], 0x3000
	s_mov_b32 s0, 0
	global_load_dword v100, v[88:89], off
	global_load_dword v101, v[88:89], off offset:2048
	global_load_dword v102, v[90:91], off
	global_load_dword v103, v[90:91], off offset:2048
	global_load_dword v104, v[92:93], off
	global_load_dword v105, v[92:93], off offset:2048
	v_lshl_add_u64 v[88:89], v[88:89], 0, s[4:5]
	v_lshl_add_u64 v[90:91], v[90:91], 0, s[4:5]
	v_lshl_add_u64 v[92:93], v[92:93], 0, s[4:5]
	global_load_dword v106, v[88:89], off
	global_load_dword v107, v[88:89], off offset:2048
	global_load_dword v108, v[90:91], off
	global_load_dword v109, v[90:91], off offset:2048
	global_load_dword v110, v[92:93], off
	global_load_dword v111, v[92:93], off offset:2048
	v_lshl_add_u64 v[88:89], v[88:89], 0, s[4:5]
	v_lshl_add_u64 v[90:91], v[90:91], 0, s[4:5]
	v_lshl_add_u64 v[92:93], v[92:93], 0, s[4:5]
	global_load_dword v112, v[88:89], off
	global_load_dword v113, v[88:89], off offset:2048
	global_load_dword v114, v[90:91], off
	global_load_dword v115, v[90:91], off offset:2048
	global_load_dword v116, v[92:93], off
	global_load_dword v117, v[92:93], off offset:2048
	v_lshl_add_u64 v[88:89], v[88:89], 0, s[4:5]
	v_lshl_add_u64 v[90:91], v[90:91], 0, s[4:5]
	v_lshl_add_u64 v[92:93], v[92:93], 0, s[4:5]
	global_load_dword v118, v[88:89], off
	global_load_dword v119, v[88:89], off offset:2048
	global_load_dword v120, v[90:91], off
	global_load_dword v121, v[90:91], off offset:2048
	global_load_dword v122, v[92:93], off
	global_load_dword v123, v[92:93], off offset:2048
	v_lshl_add_u64 v[88:89], v[88:89], 0, s[4:5]
	v_lshl_add_u64 v[90:91], v[90:91], 0, s[4:5]
	v_lshl_add_u64 v[92:93], v[92:93], 0, s[4:5]
; DI void filter_item(const PX& p, int it, float* sm) {
;     ...
; #pragma unroll 4
;   for (int k = 0; k < 64; k++) {
;     float wv[6];
; #pragma unroll
;     for (int q6 = 0; q6 < 6; q6++) wv[q6] = w3[k * 3072 + tid + NTHR * q6];
; #pragma unroll
;     for (int q = 0; q < 8; q++) {
;       const float hv = h2[q * 64 + k];
; #pragma unroll
;       for (int q6 = 0; q6 < 6; q6++) sacc[q6][q] += hv * wv[q6];
;     }
;   }
.LBB0_879:
	v_mov_b32_e32 v0, s8
	ds_read_b128 v[56:59], v0
	ds_read_b128 v[60:63], v0 offset:256
	ds_read_b128 v[64:67], v0 offset:512
	ds_read_b128 v[68:71], v0 offset:768
	ds_read_b128 v[72:75], v0 offset:1024
	ds_read_b128 v[76:79], v0 offset:1280
	ds_read_b128 v[80:83], v0 offset:1536
	ds_read_b128 v[84:87], v0 offset:1792
	global_load_dword v124, v[88:89], off
	global_load_dword v125, v[88:89], off offset:2048
	global_load_dword v126, v[90:91], off
	global_load_dword v127, v[90:91], off offset:2048
	global_load_dword v128, v[92:93], off
	global_load_dword v129, v[92:93], off offset:2048
	v_lshl_add_u64 v[88:89], v[88:89], 0, s[4:5]
	v_lshl_add_u64 v[90:91], v[90:91], 0, s[4:5]
	v_lshl_add_u64 v[92:93], v[92:93], 0, s[4:5]
	global_load_dword v130, v[88:89], off
	global_load_dword v131, v[88:89], off offset:2048
	global_load_dword v132, v[90:91], off
	global_load_dword v133, v[90:91], off offset:2048
	global_load_dword v134, v[92:93], off
	global_load_dword v135, v[92:93], off offset:2048
	v_lshl_add_u64 v[88:89], v[88:89], 0, s[4:5]
	v_lshl_add_u64 v[90:91], v[90:91], 0, s[4:5]
	v_lshl_add_u64 v[92:93], v[92:93], 0, s[4:5]
	global_load_dword v136, v[88:89], off
	global_load_dword v137, v[88:89], off offset:2048
	global_load_dword v138, v[90:91], off
	global_load_dword v139, v[90:91], off offset:2048
	global_load_dword v140, v[92:93], off
	global_load_dword v141, v[92:93], off offset:2048
	v_lshl_add_u64 v[88:89], v[88:89], 0, s[4:5]
	v_lshl_add_u64 v[90:91], v[90:91], 0, s[4:5]
	v_lshl_add_u64 v[92:93], v[92:93], 0, s[4:5]
	global_load_dword v142, v[88:89], off
	global_load_dword v143, v[88:89], off offset:2048
	global_load_dword v144, v[90:91], off
	global_load_dword v145, v[90:91], off offset:2048
	global_load_dword v146, v[92:93], off
	global_load_dword v147, v[92:93], off offset:2048
	v_lshl_add_u64 v[88:89], v[88:89], 0, s[4:5]
	v_lshl_add_u64 v[90:91], v[90:91], 0, s[4:5]
	v_lshl_add_u64 v[92:93], v[92:93], 0, s[4:5]
	s_waitcnt vmcnt(24)
	s_waitcnt lgkmcnt(0)
	v_fmac_f32_e32 v49, v100, v56
	v_fmac_f32_e32 v48, v100, v60
	v_fmac_f32_e32 v47, v100, v64
	v_fmac_f32_e32 v46, v100, v68
	v_fmac_f32_e32 v45, v100, v72
	v_fmac_f32_e32 v44, v100, v76
	v_fmac_f32_e32 v43, v100, v80
	v_fmac_f32_e32 v42, v100, v84
	v_fmac_f32_e32 v41, v101, v56
	v_fmac_f32_e32 v40, v101, v60
	v_fmac_f32_e32 v39, v101, v64
	v_fmac_f32_e32 v38, v101, v68
	v_fmac_f32_e32 v37, v101, v72
	v_fmac_f32_e32 v36, v101, v76
	v_fmac_f32_e32 v35, v101, v80
	v_fmac_f32_e32 v34, v101, v84
	v_fmac_f32_e32 v33, v102, v56
	v_fmac_f32_e32 v32, v102, v60
	v_fmac_f32_e32 v31, v102, v64
	v_fmac_f32_e32 v30, v102, v68
	v_fmac_f32_e32 v29, v102, v72
	v_fmac_f32_e32 v28, v102, v76
	v_fmac_f32_e32 v27, v102, v80
	v_fmac_f32_e32 v26, v102, v84
	v_fmac_f32_e32 v25, v103, v56
	v_fmac_f32_e32 v24, v103, v60
	v_fmac_f32_e32 v23, v103, v64
	v_fmac_f32_e32 v22, v103, v68
	v_fmac_f32_e32 v21, v103, v72
	v_fmac_f32_e32 v20, v103, v76
	v_fmac_f32_e32 v19, v103, v80
	v_fmac_f32_e32 v18, v103, v84
	v_fmac_f32_e32 v17, v104, v56
	v_fmac_f32_e32 v16, v104, v60
	v_fmac_f32_e32 v15, v104, v64
	v_fmac_f32_e32 v14, v104, v68
	v_fmac_f32_e32 v13, v104, v72
	v_fmac_f32_e32 v12, v104, v76
	v_fmac_f32_e32 v11, v104, v80
	v_fmac_f32_e32 v10, v104, v84
	v_fmac_f32_e32 v9, v105, v56
	v_fmac_f32_e32 v8, v105, v60
	v_fmac_f32_e32 v6, v105, v64
	v_fmac_f32_e32 v7, v105, v68
	v_fmac_f32_e32 v4, v105, v72
	v_fmac_f32_e32 v5, v105, v76
	v_fmac_f32_e32 v2, v105, v80
	v_fmac_f32_e32 v3, v105, v84
	v_fmac_f32_e32 v49, v106, v57
	v_fmac_f32_e32 v48, v106, v61
	v_fmac_f32_e32 v47, v106, v65
	v_fmac_f32_e32 v46, v106, v69
	v_fmac_f32_e32 v45, v106, v73
	v_fmac_f32_e32 v44, v106, v77
	v_fmac_f32_e32 v43, v106, v81
	v_fmac_f32_e32 v42, v106, v85
	v_fmac_f32_e32 v41, v107, v57
	v_fmac_f32_e32 v40, v107, v61
	v_fmac_f32_e32 v39, v107, v65
	v_fmac_f32_e32 v38, v107, v69
	v_fmac_f32_e32 v37, v107, v73
	v_fmac_f32_e32 v36, v107, v77
	v_fmac_f32_e32 v35, v107, v81
	v_fmac_f32_e32 v34, v107, v85
	v_fmac_f32_e32 v33, v108, v57
	v_fmac_f32_e32 v32, v108, v61
	v_fmac_f32_e32 v31, v108, v65
	v_fmac_f32_e32 v30, v108, v69
	v_fmac_f32_e32 v29, v108, v73
	v_fmac_f32_e32 v28, v108, v77
	v_fmac_f32_e32 v27, v108, v81
	v_fmac_f32_e32 v26, v108, v85
	v_fmac_f32_e32 v25, v109, v57
	v_fmac_f32_e32 v24, v109, v61
	v_fmac_f32_e32 v23, v109, v65
	v_fmac_f32_e32 v22, v109, v69
	v_fmac_f32_e32 v21, v109, v73
	v_fmac_f32_e32 v20, v109, v77
	v_fmac_f32_e32 v19, v109, v81
	v_fmac_f32_e32 v18, v109, v85
	v_fmac_f32_e32 v17, v110, v57
	v_fmac_f32_e32 v16, v110, v61
	v_fmac_f32_e32 v15, v110, v65
	v_fmac_f32_e32 v14, v110, v69
	v_fmac_f32_e32 v13, v110, v73
	v_fmac_f32_e32 v12, v110, v77
	v_fmac_f32_e32 v11, v110, v81
	v_fmac_f32_e32 v10, v110, v85
	v_fmac_f32_e32 v9, v111, v57
	v_fmac_f32_e32 v8, v111, v61
	v_fmac_f32_e32 v6, v111, v65
	v_fmac_f32_e32 v7, v111, v69
	v_fmac_f32_e32 v4, v111, v73
	v_fmac_f32_e32 v5, v111, v77
	v_fmac_f32_e32 v2, v111, v81
	v_fmac_f32_e32 v3, v111, v85
	v_fmac_f32_e32 v49, v112, v58
; DI void filter_item(const PX& p, int it, float* sm) {
;     ...
; #pragma unroll 4
;   for (int k = 0; k < 64; k++) {
;     float wv[6];
; #pragma unroll
;     for (int q6 = 0; q6 < 6; q6++) wv[q6] = w3[k * 3072 + tid + NTHR * q6];
; #pragma unroll
;     for (int q = 0; q < 8; q++) {
;       const float hv = h2[q * 64 + k];
; #pragma unroll
;       for (int q6 = 0; q6 < 6; q6++) sacc[q6][q] += hv * wv[q6];
;     }
;   }
	v_fmac_f32_e32 v48, v112, v62
	v_fmac_f32_e32 v47, v112, v66
	v_fmac_f32_e32 v46, v112, v70
	v_fmac_f32_e32 v45, v112, v74
	v_fmac_f32_e32 v44, v112, v78
	v_fmac_f32_e32 v43, v112, v82
	v_fmac_f32_e32 v42, v112, v86
	v_fmac_f32_e32 v41, v113, v58
	v_fmac_f32_e32 v40, v113, v62
	v_fmac_f32_e32 v39, v113, v66
	v_fmac_f32_e32 v38, v113, v70
	v_fmac_f32_e32 v37, v113, v74
	v_fmac_f32_e32 v36, v113, v78
	v_fmac_f32_e32 v35, v113, v82
	v_fmac_f32_e32 v34, v113, v86
	v_fmac_f32_e32 v33, v114, v58
	v_fmac_f32_e32 v32, v114, v62
	v_fmac_f32_e32 v31, v114, v66
	v_fmac_f32_e32 v30, v114, v70
	v_fmac_f32_e32 v29, v114, v74
	v_fmac_f32_e32 v28, v114, v78
	v_fmac_f32_e32 v27, v114, v82
	v_fmac_f32_e32 v26, v114, v86
	v_fmac_f32_e32 v25, v115, v58
	v_fmac_f32_e32 v24, v115, v62
	v_fmac_f32_e32 v23, v115, v66
	v_fmac_f32_e32 v22, v115, v70
	v_fmac_f32_e32 v21, v115, v74
	v_fmac_f32_e32 v20, v115, v78
	v_fmac_f32_e32 v19, v115, v82
	v_fmac_f32_e32 v18, v115, v86
	v_fmac_f32_e32 v17, v116, v58
	v_fmac_f32_e32 v16, v116, v62
	v_fmac_f32_e32 v15, v116, v66
	v_fmac_f32_e32 v14, v116, v70
	v_fmac_f32_e32 v13, v116, v74
	v_fmac_f32_e32 v12, v116, v78
	v_fmac_f32_e32 v11, v116, v82
	v_fmac_f32_e32 v10, v116, v86
	v_fmac_f32_e32 v9, v117, v58
	v_fmac_f32_e32 v8, v117, v62
	v_fmac_f32_e32 v6, v117, v66
	v_fmac_f32_e32 v7, v117, v70
	v_fmac_f32_e32 v4, v117, v74
	v_fmac_f32_e32 v5, v117, v78
	v_fmac_f32_e32 v2, v117, v82
	v_fmac_f32_e32 v3, v117, v86
	v_fmac_f32_e32 v49, v118, v59
	v_fmac_f32_e32 v48, v118, v63
	v_fmac_f32_e32 v47, v118, v67
	v_fmac_f32_e32 v46, v118, v71
	v_fmac_f32_e32 v45, v118, v75
	v_fmac_f32_e32 v44, v118, v79
	v_fmac_f32_e32 v43, v118, v83
	v_fmac_f32_e32 v42, v118, v87
	v_fmac_f32_e32 v41, v119, v59
	v_fmac_f32_e32 v40, v119, v63
	v_fmac_f32_e32 v39, v119, v67
	v_fmac_f32_e32 v38, v119, v71
	v_fmac_f32_e32 v37, v119, v75
	v_fmac_f32_e32 v36, v119, v79
	v_fmac_f32_e32 v35, v119, v83
	v_fmac_f32_e32 v34, v119, v87
	v_fmac_f32_e32 v33, v120, v59
	v_fmac_f32_e32 v32, v120, v63
	v_fmac_f32_e32 v31, v120, v67
	v_fmac_f32_e32 v30, v120, v71
	v_fmac_f32_e32 v29, v120, v75
	v_fmac_f32_e32 v28, v120, v79
	v_fmac_f32_e32 v27, v120, v83
	v_fmac_f32_e32 v26, v120, v87
	v_fmac_f32_e32 v25, v121, v59
	v_fmac_f32_e32 v24, v121, v63
	v_fmac_f32_e32 v23, v121, v67
	v_fmac_f32_e32 v22, v121, v71
	v_fmac_f32_e32 v21, v121, v75
	v_fmac_f32_e32 v20, v121, v79
	v_fmac_f32_e32 v19, v121, v83
	v_fmac_f32_e32 v18, v121, v87
	v_fmac_f32_e32 v17, v122, v59
	v_fmac_f32_e32 v16, v122, v63
	v_fmac_f32_e32 v15, v122, v67
	v_fmac_f32_e32 v14, v122, v71
	v_fmac_f32_e32 v13, v122, v75
	v_fmac_f32_e32 v12, v122, v79
	v_fmac_f32_e32 v11, v122, v83
	v_fmac_f32_e32 v10, v122, v87
	v_fmac_f32_e32 v9, v123, v59
	v_fmac_f32_e32 v8, v123, v63
	v_fmac_f32_e32 v6, v123, v67
	v_fmac_f32_e32 v7, v123, v71
	v_fmac_f32_e32 v4, v123, v75
	v_fmac_f32_e32 v5, v123, v79
	v_fmac_f32_e32 v2, v123, v83
	v_fmac_f32_e32 v3, v123, v87
	s_add_i32 s8, s8, 16
	v_mov_b32_e32 v0, s8
	ds_read_b128 v[56:59], v0
	ds_read_b128 v[60:63], v0 offset:256
	ds_read_b128 v[64:67], v0 offset:512
	ds_read_b128 v[68:71], v0 offset:768
	ds_read_b128 v[72:75], v0 offset:1024
	ds_read_b128 v[76:79], v0 offset:1280
	ds_read_b128 v[80:83], v0 offset:1536
	ds_read_b128 v[84:87], v0 offset:1792
	s_cmp_eq_u32 s0, 7
	s_cbranch_scc1 .Lw3_nopf
	global_load_dword v100, v[88:89], off
	global_load_dword v101, v[88:89], off offset:2048
	global_load_dword v102, v[90:91], off
	global_load_dword v103, v[90:91], off offset:2048
	global_load_dword v104, v[92:93], off
	global_load_dword v105, v[92:93], off offset:2048
	v_lshl_add_u64 v[88:89], v[88:89], 0, s[4:5]
	v_lshl_add_u64 v[90:91], v[90:91], 0, s[4:5]
	v_lshl_add_u64 v[92:93], v[92:93], 0, s[4:5]
	global_load_dword v106, v[88:89], off
	global_load_dword v107, v[88:89], off offset:2048
	global_load_dword v108, v[90:91], off
	global_load_dword v109, v[90:91], off offset:2048
	global_load_dword v110, v[92:93], off
	global_load_dword v111, v[92:93], off offset:2048
	v_lshl_add_u64 v[88:89], v[88:89], 0, s[4:5]
	v_lshl_add_u64 v[90:91], v[90:91], 0, s[4:5]
	v_lshl_add_u64 v[92:93], v[92:93], 0, s[4:5]
	global_load_dword v112, v[88:89], off
	global_load_dword v113, v[88:89], off offset:2048
	global_load_dword v114, v[90:91], off
	global_load_dword v115, v[90:91], off offset:2048
	global_load_dword v116, v[92:93], off
	global_load_dword v117, v[92:93], off offset:2048
	v_lshl_add_u64 v[88:89], v[88:89], 0, s[4:5]
	v_lshl_add_u64 v[90:91], v[90:91], 0, s[4:5]
	v_lshl_add_u64 v[92:93], v[92:93], 0, s[4:5]
	global_load_dword v118, v[88:89], off
	global_load_dword v119, v[88:89], off offset:2048
	global_load_dword v120, v[90:91], off
	global_load_dword v121, v[90:91], off offset:2048
	global_load_dword v122, v[92:93], off
	global_load_dword v123, v[92:93], off offset:2048
	v_lshl_add_u64 v[88:89], v[88:89], 0, s[4:5]
	v_lshl_add_u64 v[90:91], v[90:91], 0, s[4:5]
	v_lshl_add_u64 v[92:93], v[92:93], 0, s[4:5]
	s_waitcnt vmcnt(24)
	s_branch .Lw3_c1

; DI void filter_item(const PX& p, int it, float* sm) {
;     ...
; #pragma unroll 4
;   for (int k = 0; k < 64; k++) {
;     float wv[6];
; #pragma unroll
;     for (int q6 = 0; q6 < 6; q6++) wv[q6] = w3[k * 3072 + tid + NTHR * q6];
; #pragma unroll
;     for (int q = 0; q < 8; q++) {
;       const float hv = h2[q * 64 + k];
; #pragma unroll
;       for (int q6 = 0; q6 < 6; q6++) sacc[q6][q] += hv * wv[q6];
;     }
;   }
.Lw3_c1:
	s_waitcnt lgkmcnt(0)
	v_fmac_f32_e32 v49, v124, v56
	v_fmac_f32_e32 v48, v124, v60
	v_fmac_f32_e32 v47, v124, v64
	v_fmac_f32_e32 v46, v124, v68
	v_fmac_f32_e32 v45, v124, v72
	v_fmac_f32_e32 v44, v124, v76
	v_fmac_f32_e32 v43, v124, v80
	v_fmac_f32_e32 v42, v124, v84
	v_fmac_f32_e32 v41, v125, v56
	v_fmac_f32_e32 v40, v125, v60
	v_fmac_f32_e32 v39, v125, v64
	v_fmac_f32_e32 v38, v125, v68
	v_fmac_f32_e32 v37, v125, v72
	v_fmac_f32_e32 v36, v125, v76
	v_fmac_f32_e32 v35, v125, v80
	v_fmac_f32_e32 v34, v125, v84
	v_fmac_f32_e32 v33, v126, v56
	v_fmac_f32_e32 v32, v126, v60
	v_fmac_f32_e32 v31, v126, v64
	v_fmac_f32_e32 v30, v126, v68
	v_fmac_f32_e32 v29, v126, v72
	v_fmac_f32_e32 v28, v126, v76
	v_fmac_f32_e32 v27, v126, v80
	v_fmac_f32_e32 v26, v126, v84
	v_fmac_f32_e32 v25, v127, v56
	v_fmac_f32_e32 v24, v127, v60
	v_fmac_f32_e32 v23, v127, v64
	v_fmac_f32_e32 v22, v127, v68
	v_fmac_f32_e32 v21, v127, v72
	v_fmac_f32_e32 v20, v127, v76
	v_fmac_f32_e32 v19, v127, v80
	v_fmac_f32_e32 v18, v127, v84
	v_fmac_f32_e32 v17, v128, v56
	v_fmac_f32_e32 v16, v128, v60
	v_fmac_f32_e32 v15, v128, v64
	v_fmac_f32_e32 v14, v128, v68
	v_fmac_f32_e32 v13, v128, v72
	v_fmac_f32_e32 v12, v128, v76
	v_fmac_f32_e32 v11, v128, v80
	v_fmac_f32_e32 v10, v128, v84
	v_fmac_f32_e32 v9, v129, v56
	v_fmac_f32_e32 v8, v129, v60
	v_fmac_f32_e32 v6, v129, v64
	v_fmac_f32_e32 v7, v129, v68
	v_fmac_f32_e32 v4, v129, v72
	v_fmac_f32_e32 v5, v129, v76
	v_fmac_f32_e32 v2, v129, v80
	v_fmac_f32_e32 v3, v129, v84
	v_fmac_f32_e32 v49, v130, v57
	v_fmac_f32_e32 v48, v130, v61
	v_fmac_f32_e32 v47, v130, v65
	v_fmac_f32_e32 v46, v130, v69
	v_fmac_f32_e32 v45, v130, v73
	v_fmac_f32_e32 v44, v130, v77
	v_fmac_f32_e32 v43, v130, v81
	v_fmac_f32_e32 v42, v130, v85
	v_fmac_f32_e32 v41, v131, v57
	v_fmac_f32_e32 v40, v131, v61
	v_fmac_f32_e32 v39, v131, v65
	v_fmac_f32_e32 v38, v131, v69
	v_fmac_f32_e32 v37, v131, v73
	v_fmac_f32_e32 v36, v131, v77
	v_fmac_f32_e32 v35, v131, v81
	v_fmac_f32_e32 v34, v131, v85
	v_fmac_f32_e32 v33, v132, v57
	v_fmac_f32_e32 v32, v132, v61
	v_fmac_f32_e32 v31, v132, v65
	v_fmac_f32_e32 v30, v132, v69
	v_fmac_f32_e32 v29, v132, v73
	v_fmac_f32_e32 v28, v132, v77
	v_fmac_f32_e32 v27, v132, v81
	v_fmac_f32_e32 v26, v132, v85
	v_fmac_f32_e32 v25, v133, v57
	v_fmac_f32_e32 v24, v133, v61
	v_fmac_f32_e32 v23, v133, v65
	v_fmac_f32_e32 v22, v133, v69
	v_fmac_f32_e32 v21, v133, v73
	v_fmac_f32_e32 v20, v133, v77
	v_fmac_f32_e32 v19, v133, v81
	v_fmac_f32_e32 v18, v133, v85
	v_fmac_f32_e32 v17, v134, v57
	v_fmac_f32_e32 v16, v134, v61
	v_fmac_f32_e32 v15, v134, v65
	v_fmac_f32_e32 v14, v134, v69
	v_fmac_f32_e32 v13, v134, v73
	v_fmac_f32_e32 v12, v134, v77
	v_fmac_f32_e32 v11, v134, v81
	v_fmac_f32_e32 v10, v134, v85
	v_fmac_f32_e32 v9, v135, v57
	v_fmac_f32_e32 v8, v135, v61
	v_fmac_f32_e32 v6, v135, v65
	v_fmac_f32_e32 v7, v135, v69
	v_fmac_f32_e32 v4, v135, v73
	v_fmac_f32_e32 v5, v135, v77
	v_fmac_f32_e32 v2, v135, v81
	v_fmac_f32_e32 v3, v135, v85
	v_fmac_f32_e32 v49, v136, v58
	v_fmac_f32_e32 v48, v136, v62
	v_fmac_f32_e32 v47, v136, v66
	v_fmac_f32_e32 v46, v136, v70
	v_fmac_f32_e32 v45, v136, v74
	v_fmac_f32_e32 v44, v136, v78
	v_fmac_f32_e32 v43, v136, v82
	v_fmac_f32_e32 v42, v136, v86
	v_fmac_f32_e32 v41, v137, v58
	v_fmac_f32_e32 v40, v137, v62
	v_fmac_f32_e32 v39, v137, v66
	v_fmac_f32_e32 v38, v137, v70
	v_fmac_f32_e32 v37, v137, v74
	v_fmac_f32_e32 v36, v137, v78
	v_fmac_f32_e32 v35, v137, v82
	v_fmac_f32_e32 v34, v137, v86
	v_fmac_f32_e32 v33, v138, v58
	v_fmac_f32_e32 v32, v138, v62
	v_fmac_f32_e32 v31, v138, v66
	v_fmac_f32_e32 v30, v138, v70
	v_fmac_f32_e32 v29, v138, v74
	v_fmac_f32_e32 v28, v138, v78
	v_fmac_f32_e32 v27, v138, v82
	v_fmac_f32_e32 v26, v138, v86
	v_fmac_f32_e32 v25, v139, v58
	v_fmac_f32_e32 v24, v139, v62
	v_fmac_f32_e32 v23, v139, v66
	v_fmac_f32_e32 v22, v139, v70
	v_fmac_f32_e32 v21, v139, v74
	v_fmac_f32_e32 v20, v139, v78
	v_fmac_f32_e32 v19, v139, v82
	v_fmac_f32_e32 v18, v139, v86
	v_fmac_f32_e32 v17, v140, v58
	v_fmac_f32_e32 v16, v140, v62
	v_fmac_f32_e32 v15, v140, v66
	v_fmac_f32_e32 v14, v140, v70
	v_fmac_f32_e32 v13, v140, v74
	v_fmac_f32_e32 v12, v140, v78
	v_fmac_f32_e32 v11, v140, v82
	v_fmac_f32_e32 v10, v140, v86
	v_fmac_f32_e32 v9, v141, v58
	v_fmac_f32_e32 v8, v141, v62
	v_fmac_f32_e32 v6, v141, v66
	v_fmac_f32_e32 v7, v141, v70
	v_fmac_f32_e32 v4, v141, v74
	v_fmac_f32_e32 v5, v141, v78
	v_fmac_f32_e32 v2, v141, v82
	v_fmac_f32_e32 v3, v141, v86
	v_fmac_f32_e32 v49, v142, v59
	v_fmac_f32_e32 v48, v142, v63
	v_fmac_f32_e32 v47, v142, v67
	v_fmac_f32_e32 v46, v142, v71
	v_fmac_f32_e32 v45, v142, v75
	v_fmac_f32_e32 v44, v142, v79
	v_fmac_f32_e32 v43, v142, v83
	v_fmac_f32_e32 v42, v142, v87
	v_fmac_f32_e32 v41, v143, v59
	v_fmac_f32_e32 v40, v143, v63
	v_fmac_f32_e32 v39, v143, v67
	v_fmac_f32_e32 v38, v143, v71
	v_fmac_f32_e32 v37, v143, v75
	v_fmac_f32_e32 v36, v143, v79
	v_fmac_f32_e32 v35, v143, v83
	v_fmac_f32_e32 v34, v143, v87
	v_fmac_f32_e32 v33, v144, v59
	v_fmac_f32_e32 v32, v144, v63
	v_fmac_f32_e32 v31, v144, v67
	v_fmac_f32_e32 v30, v144, v71
	v_fmac_f32_e32 v29, v144, v75
	v_fmac_f32_e32 v28, v144, v79
	v_fmac_f32_e32 v27, v144, v83
	v_fmac_f32_e32 v26, v144, v87
	v_fmac_f32_e32 v25, v145, v59
	v_fmac_f32_e32 v24, v145, v63
	v_fmac_f32_e32 v23, v145, v67
	v_fmac_f32_e32 v22, v145, v71
	v_fmac_f32_e32 v21, v145, v75
	v_fmac_f32_e32 v20, v145, v79
	v_fmac_f32_e32 v19, v145, v83
	v_fmac_f32_e32 v18, v145, v87
	v_fmac_f32_e32 v17, v146, v59
	v_fmac_f32_e32 v16, v146, v63
	v_fmac_f32_e32 v15, v146, v67
	v_fmac_f32_e32 v14, v146, v71
	v_fmac_f32_e32 v13, v146, v75
	v_fmac_f32_e32 v12, v146, v79
	v_fmac_f32_e32 v11, v146, v83
	v_fmac_f32_e32 v10, v146, v87
	v_fmac_f32_e32 v9, v147, v59
	v_fmac_f32_e32 v8, v147, v63
	v_fmac_f32_e32 v6, v147, v67
	v_fmac_f32_e32 v7, v147, v71
	v_fmac_f32_e32 v4, v147, v75
	v_fmac_f32_e32 v5, v147, v79
	v_fmac_f32_e32 v2, v147, v83
	v_fmac_f32_e32 v3, v147, v87
	s_add_i32 s8, s8, 16
	s_add_i32 s0, s0, 1
	s_cmp_lg_u32 s0, 8
	s_cbranch_scc1 .LBB0_879
; DI void filter_item(const PX& p, int it, float* sm) {
;     ...
; #pragma unroll
;   for (int q6 = 0; q6 < 6; q6++) {
;     const int n = tid + NTHR * q6;
;     const int o = n / 1536, dir = (n % 1536) / 768, c = n % 768;
;     const float dc = fabsf(p.in[15][(l * 2 + o) * 768 + c]);
;     bfu* Rc = R + (size_t)(o * 768 + c) * (2 * L);
; #pragma unroll
;     for (int q = 0; q < 8; q++) {
;       const int jj = j0 + q;
;       const float tq = (float)jj / (float)(L - 1);
;       const float val = sacc[q6][q] * expf(-tq * dc);
;       if (dir == 0) Rc[L - jj] = f2bf(val);
;       else if (jj > 0) Rc[L + jj] = f2bf(val);
;     }
	v_readlane_b32 s4, v253, 31
	s_lshl_b32 s0, s4, 1
	s_mov_b32 s4, 0x2aaaaaab
	v_mul_hi_i32 v50, v54, s4
	v_ashrrev_i32_e32 v0, 8, v50
	v_lshrrev_b32_e32 v51, 31, v50
	v_lshrrev_b32_e32 v50, 7, v50
	v_add_u32_e32 v50, v50, v51
	s_movk_i32 s4, 0x300
	v_add_u32_e32 v0, v0, v51
	v_mul_lo_u32 v50, v50, s4
	v_sub_u32_e32 v50, v54, v50
	v_add_u32_e32 v51, s0, v0
	v_mad_i32_i24 v52, v51, s4, v50
	v_readlane_b32 s8, v252, 19
	v_ashrrev_i32_e32 v53, 31, v52
	v_readlane_b32 s22, v252, 33
	v_readlane_b32 s23, v252, 34
	v_cvt_f32_u32_e32 v57, s2
	v_readlane_b32 s5, v253, 32
	v_lshl_add_u64 v[52:53], v[52:53], 2, s[22:23]
	global_load_dword v56, v[52:53], off
	v_div_scale_f32 v52, s[4:5], v55, v55, -v57
	v_rcp_f32_e32 v53, v52
	v_mul_i32_i24_e32 v51, 0x600, v0
	v_sub_u32_e32 v51, v54, v51
	v_add_u32_e32 v51, 0x2ff, v51
	s_movk_i32 s4, 0x5fe
	v_cmp_lt_u32_e64 s[4:5], s4, v51
	v_fma_f32 v51, -v52, v53, 1.0
	v_fmac_f32_e32 v53, v51, v53
	v_div_scale_f32 v51, vcc, -v57, v55, -v57
	v_mul_f32_e32 v58, v51, v53
	v_fma_f32 v59, -v52, v58, v51
	v_fmac_f32_e32 v58, v59, v53
	v_readlane_b32 s9, v252, 20
	v_fma_f32 v51, -v52, v58, v51
	s_movk_i32 s24, 0x300
	v_readlane_b32 s10, v252, 21
	v_readlane_b32 s11, v252, 22
	v_div_fmas_f32 v58, v51, v53, v58
	s_mov_b64 s[8:9], 0
	v_readlane_b32 s12, v252, 23
	v_readlane_b32 s13, v252, 24
	v_readlane_b32 s14, v252, 25
	v_readlane_b32 s15, v252, 26
	v_readlane_b32 s16, v252, 27
	v_readlane_b32 s17, v252, 28
	v_readlane_b32 s18, v252, 29
	v_readlane_b32 s19, v252, 30
	v_readlane_b32 s20, v252, 31
	v_readlane_b32 s21, v252, 32
	s_and_saveexec_b64 s[10:11], s[4:5]
	s_xor_b64 s[10:11], exec, s[10:11]
	s_cbranch_execz .LBB0_884
	s_cmp_lg_u32 s2, 0
	s_cbranch_scc0 .LBB0_883
	v_readlane_b32 s8, v253, 31
	v_readlane_b32 s9, v253, 32
	s_add_i32 s8, s3, s2
	v_writelane_b32 v253, s8, 31
	s_nop 1
	v_writelane_b32 v253, s9, 32
	s_mov_b64 s[8:9], -1
